# GEMM k-loops: LDS-DMA stage of A(buf0,half0) moved from phase 2 to phase 3 (4/4 loads instead of 6/2), vmcnt(6) at phase 2/4 waits, all six GEMM loops
# speedup vs baseline: 1.0455x; 1.0052x over previous
.LBB0_107:
	s_or_b64 exec, exec, s[4:5]
	s_load_dwordx16 s[36:51], s[0:1], 0x40
	s_cmpk_gt_i32 s64, 0x7fff
	v_lshlrev_b32_e32 v128, 2, v129
	v_mbcnt_lo_u32_b32 v165, -1, 0
	s_waitcnt lgkmcnt(0)
	s_barrier
	s_cbranch_scc1 .LBB0_110
	v_lshlrev_b32_e32 v120, 2, v128
	v_lshlrev_b32_e32 v121, 3, v129
	s_mov_b32 s65, s64
	s_lshl_b32 s13, s12, 12
	s_lshl_b32 s98, s12, 11
	s_lshl_b32 s0, s64, 12
	s_add_u32 s0, s16, s0
	s_addc_u32 s1, s17, 0
	s_lshl_b32 s4, s64, 11
	s_add_u32 s4, s62, s4
	s_addc_u32 s5, s63, 0
	s_add_u32 s4, s4, 0x2800000
	s_addc_u32 s5, s5, 0
	s_mov_b32 s99, -1
	s_mov_b32 s18, s0
	s_mov_b32 s19, s1
	global_load_dwordx4 v[0:3], v120, s[18:19] offset:0
	global_load_dwordx4 v[4:7], v120, s[18:19] offset:1024
	global_load_dwordx4 v[8:11], v120, s[18:19] offset:2048
	global_load_dwordx4 v[12:15], v120, s[18:19] offset:3072
	global_load_dwordx4 v[64:67], v120, s[24:25] offset:0
	global_load_dwordx4 v[68:71], v120, s[24:25] offset:1024
	global_load_dwordx4 v[72:75], v120, s[24:25] offset:2048
	global_load_dwordx4 v[76:79], v120, s[24:25] offset:3072
	s_mul_i32 s100, s12, 1
	s_add_u32 s100, s64, s100
	s_cmp_lt_u32 s100, 0x8000
	s_cbranch_scc1 .Lp1_pro_ok1
	s_mov_b32 s18, s0
	s_mov_b32 s19, s1
	s_branch .Lp1_pro_ld1
.Lp1_pro_ok1:
	s_mul_i32 s18, s13, 1
	s_add_u32 s18, s0, s18
	s_addc_u32 s19, s1, 0
.Lp1_pro_ld1:
	global_load_dwordx4 v[16:19], v120, s[18:19] offset:0
	global_load_dwordx4 v[20:23], v120, s[18:19] offset:1024
	global_load_dwordx4 v[24:27], v120, s[18:19] offset:2048
	global_load_dwordx4 v[28:31], v120, s[18:19] offset:3072
	s_mul_i32 s100, s12, 2
	s_add_u32 s100, s64, s100
	s_cmp_lt_u32 s100, 0x8000
	s_cbranch_scc1 .Lp1_pro_ok2
	s_mov_b32 s18, s0
	s_mov_b32 s19, s1
	s_branch .Lp1_pro_ld2
.Lp1_pro_ok2:
	s_mul_i32 s18, s13, 2
	s_add_u32 s18, s0, s18
	s_addc_u32 s19, s1, 0
.Lp1_pro_ld2:
	global_load_dwordx4 v[32:35], v120, s[18:19] offset:0
	global_load_dwordx4 v[36:39], v120, s[18:19] offset:1024
	global_load_dwordx4 v[40:43], v120, s[18:19] offset:2048
	global_load_dwordx4 v[44:47], v120, s[18:19] offset:3072
.Lp1_row_r0:
	s_lshr_b32 s100, s65, 13
	s_cmp_eq_u32 s100, s99
	s_cbranch_scc1 .Lp1_nov_r0
	s_mov_b32 s99, s100
	s_mul_i32 s100, s100, 0x6000
	s_add_u32 s8, s6, s100
	s_addc_u32 s9, s7, 0
	s_add_u32 s18, s8, 0x1000
	s_addc_u32 s19, s9, 0
	global_load_dwordx4 v[80:83], v120, s[18:19] offset:0
	global_load_dwordx4 v[84:87], v120, s[18:19] offset:1024
	global_load_dwordx4 v[88:91], v120, s[18:19] offset:2048
	global_load_dwordx4 v[92:95], v120, s[18:19] offset:3072
	global_load_dwordx4 v[96:99], v120, s[8:9] offset:0
	global_load_dwordx4 v[100:103], v120, s[8:9] offset:1024
	global_load_dwordx4 v[104:107], v120, s[8:9] offset:2048
	global_load_dwordx4 v[108:111], v120, s[8:9] offset:3072
	s_mov_b32 s101, 1
	s_branch .Lp1_pf_r0

.Lp1_pf_r0:
	s_mul_i32 s100, s12, 3
	s_add_u32 s100, s65, s100
	s_cmp_lt_u32 s100, 0x8000
	s_cbranch_scc1 .Lp1_adv_r0
	s_mov_b32 s18, s0
	s_mov_b32 s19, s1
	s_branch .Lp1_ld_r0
.Lp1_adv_r0:
	s_mul_i32 s18, s13, 3
	s_add_u32 s18, s0, s18
	s_addc_u32 s19, s1, 0
.Lp1_ld_r0:
	global_load_dwordx4 v[48:51], v120, s[18:19] offset:0
	global_load_dwordx4 v[52:55], v120, s[18:19] offset:1024
	global_load_dwordx4 v[56:59], v120, s[18:19] offset:2048
	global_load_dwordx4 v[60:63], v120, s[18:19] offset:3072
	s_cmp_eq_u32 s101, 0
	s_cbranch_scc1 .Lp1_w8_r0
	s_waitcnt vmcnt(4)
	v_add_f32_e32 v80, 1.0, v80
	v_add_f32_e32 v81, 1.0, v81
	v_add_f32_e32 v82, 1.0, v82
	v_add_f32_e32 v83, 1.0, v83
	v_add_f32_e32 v84, 1.0, v84
	v_add_f32_e32 v85, 1.0, v85
	v_add_f32_e32 v86, 1.0, v86
	v_add_f32_e32 v87, 1.0, v87
	v_add_f32_e32 v88, 1.0, v88
	v_add_f32_e32 v89, 1.0, v89
	v_add_f32_e32 v90, 1.0, v90
	v_add_f32_e32 v91, 1.0, v91
	v_add_f32_e32 v92, 1.0, v92
	v_add_f32_e32 v93, 1.0, v93
	v_add_f32_e32 v94, 1.0, v94
	v_add_f32_e32 v95, 1.0, v95
	s_branch .Lp1_go_r0
.Lp1_w8_r0:
	s_waitcnt vmcnt(24)
.Lp1_go_r0:
	v_mul_f32_e32 v122, v0, v0
	v_fmac_f32_e32 v122, v1, v1
	v_fmac_f32_e32 v122, v2, v2
	v_fmac_f32_e32 v122, v3, v3
	v_fmac_f32_e32 v122, v4, v4
	v_fmac_f32_e32 v122, v5, v5
	v_fmac_f32_e32 v122, v6, v6
	v_fmac_f32_e32 v122, v7, v7
	v_fmac_f32_e32 v122, v8, v8
	v_fmac_f32_e32 v122, v9, v9
	v_fmac_f32_e32 v122, v10, v10
	v_fmac_f32_e32 v122, v11, v11
	v_fmac_f32_e32 v122, v12, v12
	v_fmac_f32_e32 v122, v13, v13
	v_fmac_f32_e32 v122, v14, v14
	v_fmac_f32_e32 v122, v15, v15
	s_nop 1
	v_add_f32_dpp v124, v122, v122 quad_perm:[1,0,3,2] row_mask:0xf bank_mask:0xf
	s_nop 1
	v_add_f32_dpp v122, v124, v124 quad_perm:[2,3,0,1] row_mask:0xf bank_mask:0xf
	s_nop 1
	v_add_f32_dpp v124, v122, v122 row_half_mirror row_mask:0xf bank_mask:0xf
	s_nop 1
	v_add_f32_dpp v122, v124, v124 row_mirror row_mask:0xf bank_mask:0xf
	s_nop 1
	v_readlane_b32 s100, v122, 0
	v_readlane_b32 s101, v122, 16
	v_readlane_b32 s18, v122, 32
	v_readlane_b32 s19, v122, 48
	s_nop 1
	v_mov_b32_e32 v124, s100
	v_add_f32_e32 v124, s101, v124
	v_mov_b32_e32 v122, s18
	v_add_f32_e32 v122, s19, v122
	v_add_f32_e32 v124, v124, v122
	v_mov_b32_e32 v122, 0x358637bd
	v_fmamk_f32 v124, v124, 0x3a800000, v122
	v_rsq_f32_e32 v123, v124
	s_nop 0
	v_mul_f32_e32 v0, v123, v0
	v_mul_f32_e32 v1, v123, v1
	v_mul_f32_e32 v2, v123, v2
	v_mul_f32_e32 v3, v123, v3
	v_mul_f32_e32 v4, v123, v4
	v_mul_f32_e32 v5, v123, v5
	v_mul_f32_e32 v6, v123, v6
	v_mul_f32_e32 v7, v123, v7
	v_mul_f32_e32 v8, v123, v8
	v_mul_f32_e32 v9, v123, v9
	v_mul_f32_e32 v10, v123, v10
	v_mul_f32_e32 v11, v123, v11
	v_mul_f32_e32 v12, v123, v12
	v_mul_f32_e32 v13, v123, v13
	v_mul_f32_e32 v14, v123, v14
	v_mul_f32_e32 v15, v123, v15
	v_mul_f32_e32 v0, v64, v0
	v_mul_f32_e32 v1, v65, v1
	v_mul_f32_e32 v2, v66, v2
	v_mul_f32_e32 v3, v67, v3
	v_mul_f32_e32 v4, v68, v4
	v_mul_f32_e32 v5, v69, v5
	v_mul_f32_e32 v6, v70, v6
	v_mul_f32_e32 v7, v71, v7
	v_mul_f32_e32 v8, v72, v8
	v_mul_f32_e32 v9, v73, v9
	v_mul_f32_e32 v10, v74, v10
	v_mul_f32_e32 v11, v75, v11
	v_mul_f32_e32 v12, v76, v12
	v_mul_f32_e32 v13, v77, v13
	v_mul_f32_e32 v14, v78, v14
	v_mul_f32_e32 v15, v79, v15
	v_fma_f32 v0, v80, v0, v96
	v_fma_f32 v1, v81, v1, v97
	v_fma_f32 v2, v82, v2, v98
	v_fma_f32 v3, v83, v3, v99
	v_fma_f32 v4, v84, v4, v100
	v_fma_f32 v5, v85, v5, v101
	v_fma_f32 v6, v86, v6, v102
	v_fma_f32 v7, v87, v7, v103
	v_fma_f32 v8, v88, v8, v104
	v_fma_f32 v9, v89, v9, v105
	v_fma_f32 v10, v90, v10, v106
	v_fma_f32 v11, v91, v11, v107
	v_fma_f32 v12, v92, v12, v108
	v_fma_f32 v13, v93, v13, v109
	v_fma_f32 v14, v94, v14, v110
	v_fma_f32 v15, v95, v15, v111
	v_cvt_pk_bf16_f32 v112, v0, v1
	v_cvt_pk_bf16_f32 v113, v2, v3
	v_cvt_pk_bf16_f32 v114, v4, v5
	v_cvt_pk_bf16_f32 v115, v6, v7
	v_cvt_pk_bf16_f32 v116, v8, v9
	v_cvt_pk_bf16_f32 v117, v10, v11
	v_cvt_pk_bf16_f32 v118, v12, v13
	v_cvt_pk_bf16_f32 v119, v14, v15
	global_store_dwordx2 v121, v[112:113], s[4:5] offset:0
	global_store_dwordx2 v121, v[114:115], s[4:5] offset:512
	global_store_dwordx2 v121, v[116:117], s[4:5] offset:1024
	global_store_dwordx2 v121, v[118:119], s[4:5] offset:1536
	s_add_u32 s65, s65, s12
	s_add_u32 s0, s0, s13
	s_addc_u32 s1, s1, 0
	s_add_u32 s4, s4, s98
	s_addc_u32 s5, s5, 0
	s_cmp_lt_u32 s65, 0x8000
	s_cbranch_scc0 .LBB0_110

.Lp1_ld_r1:
	global_load_dwordx4 v[0:3], v120, s[18:19] offset:0
	global_load_dwordx4 v[4:7], v120, s[18:19] offset:1024
	global_load_dwordx4 v[8:11], v120, s[18:19] offset:2048
	global_load_dwordx4 v[12:15], v120, s[18:19] offset:3072
	s_cmp_eq_u32 s101, 0
	s_cbranch_scc1 .Lp1_w8_r1
	s_waitcnt vmcnt(4)
	v_add_f32_e32 v80, 1.0, v80
	v_add_f32_e32 v81, 1.0, v81
	v_add_f32_e32 v82, 1.0, v82
	v_add_f32_e32 v83, 1.0, v83
	v_add_f32_e32 v84, 1.0, v84
	v_add_f32_e32 v85, 1.0, v85
	v_add_f32_e32 v86, 1.0, v86
	v_add_f32_e32 v87, 1.0, v87
	v_add_f32_e32 v88, 1.0, v88
	v_add_f32_e32 v89, 1.0, v89
	v_add_f32_e32 v90, 1.0, v90
	v_add_f32_e32 v91, 1.0, v91
	v_add_f32_e32 v92, 1.0, v92
	v_add_f32_e32 v93, 1.0, v93
	v_add_f32_e32 v94, 1.0, v94
	v_add_f32_e32 v95, 1.0, v95
	s_branch .Lp1_go_r1

.Lp1_go_r1:
	v_mul_f32_e32 v122, v16, v16
	v_fmac_f32_e32 v122, v17, v17
	v_fmac_f32_e32 v122, v18, v18
	v_fmac_f32_e32 v122, v19, v19
	v_fmac_f32_e32 v122, v20, v20
	v_fmac_f32_e32 v122, v21, v21
	v_fmac_f32_e32 v122, v22, v22
	v_fmac_f32_e32 v122, v23, v23
	v_fmac_f32_e32 v122, v24, v24
	v_fmac_f32_e32 v122, v25, v25
	v_fmac_f32_e32 v122, v26, v26
	v_fmac_f32_e32 v122, v27, v27
	v_fmac_f32_e32 v122, v28, v28
	v_fmac_f32_e32 v122, v29, v29
	v_fmac_f32_e32 v122, v30, v30
	v_fmac_f32_e32 v122, v31, v31
	s_nop 1
	v_add_f32_dpp v124, v122, v122 quad_perm:[1,0,3,2] row_mask:0xf bank_mask:0xf
	s_nop 1
	v_add_f32_dpp v122, v124, v124 quad_perm:[2,3,0,1] row_mask:0xf bank_mask:0xf
	s_nop 1
	v_add_f32_dpp v124, v122, v122 row_half_mirror row_mask:0xf bank_mask:0xf
	s_nop 1
	v_add_f32_dpp v122, v124, v124 row_mirror row_mask:0xf bank_mask:0xf
	s_nop 1
	v_readlane_b32 s100, v122, 0
	v_readlane_b32 s101, v122, 16
	v_readlane_b32 s18, v122, 32
	v_readlane_b32 s19, v122, 48
	s_nop 1
	v_mov_b32_e32 v124, s100
	v_add_f32_e32 v124, s101, v124
	v_mov_b32_e32 v122, s18
	v_add_f32_e32 v122, s19, v122
	v_add_f32_e32 v124, v124, v122
	v_mov_b32_e32 v122, 0x358637bd
	v_fmamk_f32 v124, v124, 0x3a800000, v122
	v_rsq_f32_e32 v123, v124
	s_nop 0
	v_mul_f32_e32 v16, v123, v16
	v_mul_f32_e32 v17, v123, v17
	v_mul_f32_e32 v18, v123, v18
	v_mul_f32_e32 v19, v123, v19
	v_mul_f32_e32 v20, v123, v20
	v_mul_f32_e32 v21, v123, v21
	v_mul_f32_e32 v22, v123, v22
	v_mul_f32_e32 v23, v123, v23
	v_mul_f32_e32 v24, v123, v24
	v_mul_f32_e32 v25, v123, v25
	v_mul_f32_e32 v26, v123, v26
	v_mul_f32_e32 v27, v123, v27
	v_mul_f32_e32 v28, v123, v28
	v_mul_f32_e32 v29, v123, v29
	v_mul_f32_e32 v30, v123, v30
	v_mul_f32_e32 v31, v123, v31
	v_mul_f32_e32 v16, v64, v16
	v_mul_f32_e32 v17, v65, v17
	v_mul_f32_e32 v18, v66, v18
	v_mul_f32_e32 v19, v67, v19
	v_mul_f32_e32 v20, v68, v20
	v_mul_f32_e32 v21, v69, v21
	v_mul_f32_e32 v22, v70, v22
	v_mul_f32_e32 v23, v71, v23
	v_mul_f32_e32 v24, v72, v24
	v_mul_f32_e32 v25, v73, v25
	v_mul_f32_e32 v26, v74, v26
	v_mul_f32_e32 v27, v75, v27
	v_mul_f32_e32 v28, v76, v28
	v_mul_f32_e32 v29, v77, v29
	v_mul_f32_e32 v30, v78, v30
	v_mul_f32_e32 v31, v79, v31
	v_fma_f32 v16, v80, v16, v96
	v_fma_f32 v17, v81, v17, v97
	v_fma_f32 v18, v82, v18, v98
	v_fma_f32 v19, v83, v19, v99
	v_fma_f32 v20, v84, v20, v100
	v_fma_f32 v21, v85, v21, v101
	v_fma_f32 v22, v86, v22, v102
	v_fma_f32 v23, v87, v23, v103
	v_fma_f32 v24, v88, v24, v104
	v_fma_f32 v25, v89, v25, v105
	v_fma_f32 v26, v90, v26, v106
	v_fma_f32 v27, v91, v27, v107
	v_fma_f32 v28, v92, v28, v108
	v_fma_f32 v29, v93, v29, v109
	v_fma_f32 v30, v94, v30, v110
	v_fma_f32 v31, v95, v31, v111
	v_cvt_pk_bf16_f32 v112, v16, v17
	v_cvt_pk_bf16_f32 v113, v18, v19
	v_cvt_pk_bf16_f32 v114, v20, v21
	v_cvt_pk_bf16_f32 v115, v22, v23
	v_cvt_pk_bf16_f32 v116, v24, v25
	v_cvt_pk_bf16_f32 v117, v26, v27
	v_cvt_pk_bf16_f32 v118, v28, v29
	v_cvt_pk_bf16_f32 v119, v30, v31
	global_store_dwordx2 v121, v[112:113], s[4:5] offset:0
	global_store_dwordx2 v121, v[114:115], s[4:5] offset:512
	global_store_dwordx2 v121, v[116:117], s[4:5] offset:1024
	global_store_dwordx2 v121, v[118:119], s[4:5] offset:1536
	s_add_u32 s65, s65, s12
	s_add_u32 s0, s0, s13
	s_addc_u32 s1, s1, 0
	s_add_u32 s4, s4, s98
	s_addc_u32 s5, s5, 0
	s_cmp_lt_u32 s65, 0x8000
	s_cbranch_scc0 .LBB0_110

.Lp1_ld_r2:
	global_load_dwordx4 v[16:19], v120, s[18:19] offset:0
	global_load_dwordx4 v[20:23], v120, s[18:19] offset:1024
	global_load_dwordx4 v[24:27], v120, s[18:19] offset:2048
	global_load_dwordx4 v[28:31], v120, s[18:19] offset:3072
	s_cmp_eq_u32 s101, 0
	s_cbranch_scc1 .Lp1_w8_r2
	s_waitcnt vmcnt(4)
	v_add_f32_e32 v80, 1.0, v80
	v_add_f32_e32 v81, 1.0, v81
	v_add_f32_e32 v82, 1.0, v82
	v_add_f32_e32 v83, 1.0, v83
	v_add_f32_e32 v84, 1.0, v84
	v_add_f32_e32 v85, 1.0, v85
	v_add_f32_e32 v86, 1.0, v86
	v_add_f32_e32 v87, 1.0, v87
	v_add_f32_e32 v88, 1.0, v88
	v_add_f32_e32 v89, 1.0, v89
	v_add_f32_e32 v90, 1.0, v90
	v_add_f32_e32 v91, 1.0, v91
	v_add_f32_e32 v92, 1.0, v92
	v_add_f32_e32 v93, 1.0, v93
	v_add_f32_e32 v94, 1.0, v94
	v_add_f32_e32 v95, 1.0, v95
	s_branch .Lp1_go_r2

.Lp1_go_r2:
	v_mul_f32_e32 v122, v32, v32
	v_fmac_f32_e32 v122, v33, v33
	v_fmac_f32_e32 v122, v34, v34
	v_fmac_f32_e32 v122, v35, v35
	v_fmac_f32_e32 v122, v36, v36
	v_fmac_f32_e32 v122, v37, v37
	v_fmac_f32_e32 v122, v38, v38
	v_fmac_f32_e32 v122, v39, v39
	v_fmac_f32_e32 v122, v40, v40
	v_fmac_f32_e32 v122, v41, v41
	v_fmac_f32_e32 v122, v42, v42
	v_fmac_f32_e32 v122, v43, v43
	v_fmac_f32_e32 v122, v44, v44
	v_fmac_f32_e32 v122, v45, v45
	v_fmac_f32_e32 v122, v46, v46
	v_fmac_f32_e32 v122, v47, v47
	s_nop 1
	v_add_f32_dpp v124, v122, v122 quad_perm:[1,0,3,2] row_mask:0xf bank_mask:0xf
	s_nop 1
	v_add_f32_dpp v122, v124, v124 quad_perm:[2,3,0,1] row_mask:0xf bank_mask:0xf
	s_nop 1
	v_add_f32_dpp v124, v122, v122 row_half_mirror row_mask:0xf bank_mask:0xf
	s_nop 1
	v_add_f32_dpp v122, v124, v124 row_mirror row_mask:0xf bank_mask:0xf
	s_nop 1
	v_readlane_b32 s100, v122, 0
	v_readlane_b32 s101, v122, 16
	v_readlane_b32 s18, v122, 32
	v_readlane_b32 s19, v122, 48
	s_nop 1
	v_mov_b32_e32 v124, s100
	v_add_f32_e32 v124, s101, v124
	v_mov_b32_e32 v122, s18
	v_add_f32_e32 v122, s19, v122
	v_add_f32_e32 v124, v124, v122
	v_mov_b32_e32 v122, 0x358637bd
	v_fmamk_f32 v124, v124, 0x3a800000, v122
	v_rsq_f32_e32 v123, v124
	s_nop 0
	v_mul_f32_e32 v32, v123, v32
	v_mul_f32_e32 v33, v123, v33
	v_mul_f32_e32 v34, v123, v34
	v_mul_f32_e32 v35, v123, v35
	v_mul_f32_e32 v36, v123, v36
	v_mul_f32_e32 v37, v123, v37
	v_mul_f32_e32 v38, v123, v38
	v_mul_f32_e32 v39, v123, v39
	v_mul_f32_e32 v40, v123, v40
	v_mul_f32_e32 v41, v123, v41
	v_mul_f32_e32 v42, v123, v42
	v_mul_f32_e32 v43, v123, v43
	v_mul_f32_e32 v44, v123, v44
	v_mul_f32_e32 v45, v123, v45
	v_mul_f32_e32 v46, v123, v46
	v_mul_f32_e32 v47, v123, v47
	v_mul_f32_e32 v32, v64, v32
	v_mul_f32_e32 v33, v65, v33
	v_mul_f32_e32 v34, v66, v34
	v_mul_f32_e32 v35, v67, v35
	v_mul_f32_e32 v36, v68, v36
	v_mul_f32_e32 v37, v69, v37
	v_mul_f32_e32 v38, v70, v38
	v_mul_f32_e32 v39, v71, v39
	v_mul_f32_e32 v40, v72, v40
	v_mul_f32_e32 v41, v73, v41
	v_mul_f32_e32 v42, v74, v42
	v_mul_f32_e32 v43, v75, v43
	v_mul_f32_e32 v44, v76, v44
	v_mul_f32_e32 v45, v77, v45
	v_mul_f32_e32 v46, v78, v46
	v_mul_f32_e32 v47, v79, v47
	v_fma_f32 v32, v80, v32, v96
	v_fma_f32 v33, v81, v33, v97
	v_fma_f32 v34, v82, v34, v98
	v_fma_f32 v35, v83, v35, v99
	v_fma_f32 v36, v84, v36, v100
	v_fma_f32 v37, v85, v37, v101
	v_fma_f32 v38, v86, v38, v102
	v_fma_f32 v39, v87, v39, v103
	v_fma_f32 v40, v88, v40, v104
	v_fma_f32 v41, v89, v41, v105
	v_fma_f32 v42, v90, v42, v106
	v_fma_f32 v43, v91, v43, v107
	v_fma_f32 v44, v92, v44, v108
	v_fma_f32 v45, v93, v45, v109
	v_fma_f32 v46, v94, v46, v110
	v_fma_f32 v47, v95, v47, v111
	v_cvt_pk_bf16_f32 v112, v32, v33
	v_cvt_pk_bf16_f32 v113, v34, v35
	v_cvt_pk_bf16_f32 v114, v36, v37
	v_cvt_pk_bf16_f32 v115, v38, v39
	v_cvt_pk_bf16_f32 v116, v40, v41
	v_cvt_pk_bf16_f32 v117, v42, v43
	v_cvt_pk_bf16_f32 v118, v44, v45
	v_cvt_pk_bf16_f32 v119, v46, v47
	global_store_dwordx2 v121, v[112:113], s[4:5] offset:0
	global_store_dwordx2 v121, v[114:115], s[4:5] offset:512
	global_store_dwordx2 v121, v[116:117], s[4:5] offset:1024
	global_store_dwordx2 v121, v[118:119], s[4:5] offset:1536
	s_add_u32 s65, s65, s12
	s_add_u32 s0, s0, s13
	s_addc_u32 s1, s1, 0
	s_add_u32 s4, s4, s98
	s_addc_u32 s5, s5, 0
	s_cmp_lt_u32 s65, 0x8000
	s_cbranch_scc0 .LBB0_110

.Lp1_ld_r3:
	global_load_dwordx4 v[32:35], v120, s[18:19] offset:0
	global_load_dwordx4 v[36:39], v120, s[18:19] offset:1024
	global_load_dwordx4 v[40:43], v120, s[18:19] offset:2048
	global_load_dwordx4 v[44:47], v120, s[18:19] offset:3072
	s_cmp_eq_u32 s101, 0
	s_cbranch_scc1 .Lp1_w8_r3
	s_waitcnt vmcnt(4)
	v_add_f32_e32 v80, 1.0, v80
	v_add_f32_e32 v81, 1.0, v81
	v_add_f32_e32 v82, 1.0, v82
	v_add_f32_e32 v83, 1.0, v83
	v_add_f32_e32 v84, 1.0, v84
	v_add_f32_e32 v85, 1.0, v85
	v_add_f32_e32 v86, 1.0, v86
	v_add_f32_e32 v87, 1.0, v87
	v_add_f32_e32 v88, 1.0, v88
	v_add_f32_e32 v89, 1.0, v89
	v_add_f32_e32 v90, 1.0, v90
	v_add_f32_e32 v91, 1.0, v91
	v_add_f32_e32 v92, 1.0, v92
	v_add_f32_e32 v93, 1.0, v93
	v_add_f32_e32 v94, 1.0, v94
	v_add_f32_e32 v95, 1.0, v95
	s_branch .Lp1_go_r3

.Lp1_go_r3:
	v_mul_f32_e32 v122, v48, v48
	v_fmac_f32_e32 v122, v49, v49
	v_fmac_f32_e32 v122, v50, v50
	v_fmac_f32_e32 v122, v51, v51
	v_fmac_f32_e32 v122, v52, v52
	v_fmac_f32_e32 v122, v53, v53
	v_fmac_f32_e32 v122, v54, v54
	v_fmac_f32_e32 v122, v55, v55
	v_fmac_f32_e32 v122, v56, v56
	v_fmac_f32_e32 v122, v57, v57
	v_fmac_f32_e32 v122, v58, v58
	v_fmac_f32_e32 v122, v59, v59
	v_fmac_f32_e32 v122, v60, v60
	v_fmac_f32_e32 v122, v61, v61
	v_fmac_f32_e32 v122, v62, v62
	v_fmac_f32_e32 v122, v63, v63
	s_nop 1
	v_add_f32_dpp v124, v122, v122 quad_perm:[1,0,3,2] row_mask:0xf bank_mask:0xf
	s_nop 1
	v_add_f32_dpp v122, v124, v124 quad_perm:[2,3,0,1] row_mask:0xf bank_mask:0xf
	s_nop 1
	v_add_f32_dpp v124, v122, v122 row_half_mirror row_mask:0xf bank_mask:0xf
	s_nop 1
	v_add_f32_dpp v122, v124, v124 row_mirror row_mask:0xf bank_mask:0xf
	s_nop 1
	v_readlane_b32 s100, v122, 0
	v_readlane_b32 s101, v122, 16
	v_readlane_b32 s18, v122, 32
	v_readlane_b32 s19, v122, 48
	s_nop 1
	v_mov_b32_e32 v124, s100
	v_add_f32_e32 v124, s101, v124
	v_mov_b32_e32 v122, s18
	v_add_f32_e32 v122, s19, v122
	v_add_f32_e32 v124, v124, v122
	v_mov_b32_e32 v122, 0x358637bd
	v_fmamk_f32 v124, v124, 0x3a800000, v122
	v_rsq_f32_e32 v123, v124
	s_nop 0
	v_mul_f32_e32 v48, v123, v48
	v_mul_f32_e32 v49, v123, v49
	v_mul_f32_e32 v50, v123, v50
	v_mul_f32_e32 v51, v123, v51
	v_mul_f32_e32 v52, v123, v52
	v_mul_f32_e32 v53, v123, v53
	v_mul_f32_e32 v54, v123, v54
	v_mul_f32_e32 v55, v123, v55
	v_mul_f32_e32 v56, v123, v56
	v_mul_f32_e32 v57, v123, v57
	v_mul_f32_e32 v58, v123, v58
	v_mul_f32_e32 v59, v123, v59
	v_mul_f32_e32 v60, v123, v60
	v_mul_f32_e32 v61, v123, v61
	v_mul_f32_e32 v62, v123, v62
	v_mul_f32_e32 v63, v123, v63
	v_mul_f32_e32 v48, v64, v48
	v_mul_f32_e32 v49, v65, v49
	v_mul_f32_e32 v50, v66, v50
	v_mul_f32_e32 v51, v67, v51
	v_mul_f32_e32 v52, v68, v52
	v_mul_f32_e32 v53, v69, v53
	v_mul_f32_e32 v54, v70, v54
	v_mul_f32_e32 v55, v71, v55
	v_mul_f32_e32 v56, v72, v56
	v_mul_f32_e32 v57, v73, v57
	v_mul_f32_e32 v58, v74, v58
	v_mul_f32_e32 v59, v75, v59
	v_mul_f32_e32 v60, v76, v60
	v_mul_f32_e32 v61, v77, v61
	v_mul_f32_e32 v62, v78, v62
	v_mul_f32_e32 v63, v79, v63
	v_fma_f32 v48, v80, v48, v96
	v_fma_f32 v49, v81, v49, v97
	v_fma_f32 v50, v82, v50, v98
	v_fma_f32 v51, v83, v51, v99
	v_fma_f32 v52, v84, v52, v100
	v_fma_f32 v53, v85, v53, v101
	v_fma_f32 v54, v86, v54, v102
	v_fma_f32 v55, v87, v55, v103
	v_fma_f32 v56, v88, v56, v104
	v_fma_f32 v57, v89, v57, v105
	v_fma_f32 v58, v90, v58, v106
	v_fma_f32 v59, v91, v59, v107
	v_fma_f32 v60, v92, v60, v108
	v_fma_f32 v61, v93, v61, v109
	v_fma_f32 v62, v94, v62, v110
	v_fma_f32 v63, v95, v63, v111
	v_cvt_pk_bf16_f32 v112, v48, v49
	v_cvt_pk_bf16_f32 v113, v50, v51
	v_cvt_pk_bf16_f32 v114, v52, v53
	v_cvt_pk_bf16_f32 v115, v54, v55
	v_cvt_pk_bf16_f32 v116, v56, v57
	v_cvt_pk_bf16_f32 v117, v58, v59
	v_cvt_pk_bf16_f32 v118, v60, v61
	v_cvt_pk_bf16_f32 v119, v62, v63
	global_store_dwordx2 v121, v[112:113], s[4:5] offset:0
	global_store_dwordx2 v121, v[114:115], s[4:5] offset:512
	global_store_dwordx2 v121, v[116:117], s[4:5] offset:1024
	global_store_dwordx2 v121, v[118:119], s[4:5] offset:1536
	s_add_u32 s65, s65, s12
	s_add_u32 s0, s0, s13
	s_addc_u32 s1, s1, 0
	s_add_u32 s4, s4, s98
	s_addc_u32 s5, s5, 0
	s_cmp_lt_u32 s65, 0x8000
	s_cbranch_scc1 .Lp1_row_r0

.LBB0_173:
	s_waitcnt lgkmcnt(0)
	ds_read_b128 v[148:151], v172
	ds_read_b128 v[152:155], v172 offset:1024
	ds_read_b128 v[156:159], v172 offset:2048
	ds_read_b128 v[160:163], v172 offset:3072
	ds_read_b128 v[178:181], v173
	ds_read_b128 v[182:185], v173 offset:1024
	ds_read_b128 v[186:189], v173 offset:2048
	ds_read_b128 v[190:193], v173 offset:3072
	s_add_u32 s7, s80, 0xfffc0080
	s_addc_u32 s24, s81, -1
	s_cmp_eq_u32 s6, 12
	s_cselect_b32 s85, s1, s24
	s_cselect_b32 s84, s75, s7
	s_cselect_b32 s83, s73, s33
	s_cselect_b32 s82, vcc_lo, vcc_hi
	v_lshl_add_u64 v[198:199], s[80:81], 0, v[140:141]
	s_add_i32 m0, s65, 0xc000
	ds_read_b128 v[194:197], v174
	ds_read_b128 v[202:205], v174 offset:1024
	ds_read_b128 v[210:213], v174 offset:2048
	ds_read_b128 v[214:217], v174 offset:3072
	ds_read_b128 v[218:221], v174 offset:4096
	ds_read_b128 v[222:225], v174 offset:5120
	ds_read_b128 v[226:229], v174 offset:6144
	ds_read_b128 v[230:233], v174 offset:7168
	global_load_lds_dwordx4 v[198:199], off
	v_lshl_add_u64 v[198:199], s[80:81], 0, v[142:143]
	s_add_i32 m0, s65, 0xe000
	s_nop 0
	global_load_lds_dwordx4 v[198:199], off
	s_waitcnt vmcnt(8)
	s_waitcnt lgkmcnt(0)
	s_barrier
	s_setprio 1
	s_waitcnt lgkmcnt(0)
	v_mfma_f32_16x16x32_bf16 v[124:127], v[148:151], v[194:197], v[124:127]
	v_mfma_f32_16x16x32_bf16 v[120:123], v[156:159], v[194:197], v[120:123]
	v_mfma_f32_16x16x32_bf16 v[112:115], v[148:151], v[210:213], v[112:115]
	v_mfma_f32_16x16x32_bf16 v[104:107], v[156:159], v[210:213], v[104:107]
	v_mfma_f32_16x16x32_bf16 v[100:103], v[148:151], v[218:221], v[100:103]
	v_mfma_f32_16x16x32_bf16 v[92:95], v[156:159], v[218:221], v[92:95]
	v_mfma_f32_16x16x32_bf16 v[84:87], v[148:151], v[226:229], v[84:87]
	v_mfma_f32_16x16x32_bf16 v[76:79], v[156:159], v[226:229], v[76:79]
	v_mfma_f32_16x16x32_bf16 v[124:127], v[152:155], v[202:205], v[124:127]
	v_mfma_f32_16x16x32_bf16 v[120:123], v[160:163], v[202:205], v[120:123]
	v_mfma_f32_16x16x32_bf16 v[112:115], v[152:155], v[214:217], v[112:115]
	v_mfma_f32_16x16x32_bf16 v[104:107], v[160:163], v[214:217], v[104:107]
	v_mfma_f32_16x16x32_bf16 v[100:103], v[152:155], v[222:225], v[100:103]
	v_mfma_f32_16x16x32_bf16 v[92:95], v[160:163], v[222:225], v[92:95]
	v_mfma_f32_16x16x32_bf16 v[84:87], v[152:155], v[230:233], v[84:87]
	v_mfma_f32_16x16x32_bf16 v[76:79], v[160:163], v[230:233], v[76:79]
	s_setprio 0
	s_setprio 1
	v_mfma_f32_16x16x32_bf16 v[116:119], v[178:181], v[194:197], v[116:119]
	v_mfma_f32_16x16x32_bf16 v[108:111], v[186:189], v[194:197], v[108:111]
	v_mfma_f32_16x16x32_bf16 v[96:99], v[178:181], v[210:213], v[96:99]
	v_mfma_f32_16x16x32_bf16 v[88:91], v[186:189], v[210:213], v[88:91]
	v_mfma_f32_16x16x32_bf16 v[80:83], v[178:181], v[218:221], v[80:83]
	v_mfma_f32_16x16x32_bf16 v[72:75], v[186:189], v[218:221], v[72:75]
	v_mfma_f32_16x16x32_bf16 v[68:71], v[178:181], v[226:229], v[68:71]
	v_mfma_f32_16x16x32_bf16 v[64:67], v[186:189], v[226:229], v[64:67]
	v_mfma_f32_16x16x32_bf16 v[116:119], v[182:185], v[202:205], v[116:119]
	v_mfma_f32_16x16x32_bf16 v[108:111], v[190:193], v[202:205], v[108:111]
	v_mfma_f32_16x16x32_bf16 v[96:99], v[182:185], v[214:217], v[96:99]
	v_mfma_f32_16x16x32_bf16 v[88:91], v[190:193], v[214:217], v[88:91]
	v_mfma_f32_16x16x32_bf16 v[80:83], v[182:185], v[222:225], v[80:83]
	v_mfma_f32_16x16x32_bf16 v[72:75], v[190:193], v[222:225], v[72:75]
	v_mfma_f32_16x16x32_bf16 v[68:71], v[182:185], v[230:233], v[68:71]
	v_mfma_f32_16x16x32_bf16 v[64:67], v[190:193], v[230:233], v[64:67]
	s_setprio 0
	s_barrier
	s_add_i32 s7, s95, s13
	v_lshl_add_u64 v[198:199], s[82:83], 0, v[132:133]
	s_mov_b32 m0, s7
	ds_read_b128 v[194:197], v174 offset:16384
	ds_read_b128 v[202:205], v174 offset:17408
	ds_read_b128 v[210:213], v174 offset:18432
	ds_read_b128 v[214:217], v174 offset:19456
	ds_read_b128 v[218:221], v174 offset:20480
	ds_read_b128 v[222:225], v174 offset:21504
	ds_read_b128 v[226:229], v174 offset:22528
	ds_read_b128 v[230:233], v174 offset:23552
	global_load_lds_dwordx4 v[198:199], off
	s_add_i32 m0, s7, 0x2000
	s_add_u32 s24, s82, 0x40000
	v_lshl_add_u64 v[206:207], s[82:83], 0, v[136:137]
	s_addc_u32 s25, s83, 0
	s_add_i32 s7, s96, s13
	global_load_lds_dwordx4 v[206:207], off
	v_lshl_add_u64 v[234:235], s[24:25], 0, v[132:133]
	s_mov_b32 m0, s7
	v_lshl_add_u64 v[236:237], s[84:85], 0, v[134:135]
	global_load_lds_dwordx4 v[234:235], off
	v_lshl_add_u64 v[234:235], s[24:25], 0, v[136:137]
	s_add_i32 m0, s7, 0x2000
	s_nop 0
	global_load_lds_dwordx4 v[234:235], off
	s_waitcnt vmcnt(6)
	s_waitcnt lgkmcnt(0)
	s_barrier
	s_setprio 1
	s_waitcnt lgkmcnt(0)
	v_mfma_f32_16x16x32_bf16 v[60:63], v[148:151], v[194:197], v[60:63]
	v_mfma_f32_16x16x32_bf16 v[56:59], v[156:159], v[194:197], v[56:59]
	v_mfma_f32_16x16x32_bf16 v[52:55], v[148:151], v[210:213], v[52:55]
	v_mfma_f32_16x16x32_bf16 v[44:47], v[156:159], v[210:213], v[44:47]
	v_mfma_f32_16x16x32_bf16 v[36:39], v[148:151], v[218:221], v[36:39]
	v_mfma_f32_16x16x32_bf16 v[28:31], v[156:159], v[218:221], v[28:31]
	v_mfma_f32_16x16x32_bf16 v[20:23], v[148:151], v[226:229], v[20:23]
	v_mfma_f32_16x16x32_bf16 v[12:15], v[156:159], v[226:229], v[12:15]
	v_mfma_f32_16x16x32_bf16 v[60:63], v[152:155], v[202:205], v[60:63]
	v_mfma_f32_16x16x32_bf16 v[56:59], v[160:163], v[202:205], v[56:59]
	v_mfma_f32_16x16x32_bf16 v[52:55], v[152:155], v[214:217], v[52:55]
	v_mfma_f32_16x16x32_bf16 v[44:47], v[160:163], v[214:217], v[44:47]
	v_mfma_f32_16x16x32_bf16 v[36:39], v[152:155], v[222:225], v[36:39]
	v_mfma_f32_16x16x32_bf16 v[28:31], v[160:163], v[222:225], v[28:31]
	v_mfma_f32_16x16x32_bf16 v[20:23], v[152:155], v[230:233], v[20:23]
	v_mfma_f32_16x16x32_bf16 v[12:15], v[160:163], v[230:233], v[12:15]
	s_setprio 0
	s_setprio 1
	v_mfma_f32_16x16x32_bf16 v[48:51], v[178:181], v[194:197], v[48:51]
	v_mfma_f32_16x16x32_bf16 v[40:43], v[186:189], v[194:197], v[40:43]
	v_mfma_f32_16x16x32_bf16 v[32:35], v[178:181], v[210:213], v[32:35]
	v_mfma_f32_16x16x32_bf16 v[24:27], v[186:189], v[210:213], v[24:27]
	v_mfma_f32_16x16x32_bf16 v[16:19], v[178:181], v[218:221], v[16:19]
	v_mfma_f32_16x16x32_bf16 v[8:11], v[186:189], v[218:221], v[8:11]
	v_mfma_f32_16x16x32_bf16 v[4:7], v[178:181], v[226:229], v[4:7]
	v_mfma_f32_16x16x32_bf16 v[0:3], v[186:189], v[226:229], v[0:3]
	v_mfma_f32_16x16x32_bf16 v[48:51], v[182:185], v[202:205], v[48:51]
	v_mfma_f32_16x16x32_bf16 v[40:43], v[190:193], v[202:205], v[40:43]
	v_mfma_f32_16x16x32_bf16 v[32:35], v[182:185], v[214:217], v[32:35]
	v_mfma_f32_16x16x32_bf16 v[24:27], v[190:193], v[214:217], v[24:27]
	v_mfma_f32_16x16x32_bf16 v[16:19], v[182:185], v[222:225], v[16:19]
	v_mfma_f32_16x16x32_bf16 v[8:11], v[190:193], v[222:225], v[8:11]
	v_mfma_f32_16x16x32_bf16 v[4:7], v[182:185], v[230:233], v[4:7]
	v_mfma_f32_16x16x32_bf16 v[0:3], v[190:193], v[230:233], v[0:3]
	s_setprio 0
	s_barrier
	s_add_i32 s7, 0, 0x18000
	v_add_u32_e32 v138, s7, v169
	s_add_i32 s86, 0, 0x1c000
	ds_read_b128 v[148:151], v138
	ds_read_b128 v[152:155], v138 offset:1024
	ds_read_b128 v[156:159], v138 offset:2048
	ds_read_b128 v[160:163], v138 offset:3072
	v_add_u32_e32 v138, s86, v169
	ds_read_b128 v[178:181], v138
	ds_read_b128 v[182:185], v138 offset:1024
	ds_read_b128 v[186:189], v138 offset:2048
	ds_read_b128 v[190:193], v138 offset:3072
	v_lshl_add_u64 v[234:235], s[84:85], 0, v[130:131]
	s_mov_b32 m0, s65
	s_nop 0
	global_load_lds_dwordx4 v[234:235], off
	s_mov_b32 m0, s69
	s_nop 0
	global_load_lds_dwordx4 v[236:237], off
	s_add_u32 s24, s84, 0x40000
	s_addc_u32 s25, s85, 0
	s_mov_b32 m0, s87
	v_lshl_add_u64 v[238:239], s[24:25], 0, v[130:131]
	ds_read_b128 v[194:197], v174 offset:32768
	ds_read_b128 v[202:205], v174 offset:33792
	ds_read_b128 v[210:213], v174 offset:34816
	ds_read_b128 v[214:217], v174 offset:35840
	ds_read_b128 v[218:221], v174 offset:36864
	ds_read_b128 v[222:225], v174 offset:37888
	ds_read_b128 v[226:229], v174 offset:38912
	ds_read_b128 v[230:233], v174 offset:39936
	global_load_lds_dwordx4 v[238:239], off
	v_lshl_add_u64 v[238:239], s[24:25], 0, v[134:135]
	s_mov_b32 m0, s88
	s_nop 0
	global_load_lds_dwordx4 v[238:239], off
	s_waitcnt vmcnt(8)
	s_waitcnt lgkmcnt(0)
	s_barrier
	s_setprio 1
	s_waitcnt lgkmcnt(0)
	v_mfma_f32_16x16x32_bf16 v[124:127], v[148:151], v[194:197], v[124:127]
	v_mfma_f32_16x16x32_bf16 v[120:123], v[156:159], v[194:197], v[120:123]
	v_mfma_f32_16x16x32_bf16 v[112:115], v[148:151], v[210:213], v[112:115]
	v_mfma_f32_16x16x32_bf16 v[104:107], v[156:159], v[210:213], v[104:107]
	v_mfma_f32_16x16x32_bf16 v[100:103], v[148:151], v[218:221], v[100:103]
	v_mfma_f32_16x16x32_bf16 v[92:95], v[156:159], v[218:221], v[92:95]
	v_mfma_f32_16x16x32_bf16 v[84:87], v[148:151], v[226:229], v[84:87]
	v_mfma_f32_16x16x32_bf16 v[76:79], v[156:159], v[226:229], v[76:79]
	v_mfma_f32_16x16x32_bf16 v[124:127], v[152:155], v[202:205], v[124:127]
	v_mfma_f32_16x16x32_bf16 v[120:123], v[160:163], v[202:205], v[120:123]
	v_mfma_f32_16x16x32_bf16 v[112:115], v[152:155], v[214:217], v[112:115]
	v_mfma_f32_16x16x32_bf16 v[104:107], v[160:163], v[214:217], v[104:107]
	v_mfma_f32_16x16x32_bf16 v[100:103], v[152:155], v[222:225], v[100:103]
	v_mfma_f32_16x16x32_bf16 v[92:95], v[160:163], v[222:225], v[92:95]
	v_mfma_f32_16x16x32_bf16 v[84:87], v[152:155], v[230:233], v[84:87]
	v_mfma_f32_16x16x32_bf16 v[76:79], v[160:163], v[230:233], v[76:79]
	s_setprio 0
	s_setprio 1
	v_mfma_f32_16x16x32_bf16 v[116:119], v[178:181], v[194:197], v[116:119]
	v_mfma_f32_16x16x32_bf16 v[108:111], v[186:189], v[194:197], v[108:111]
	v_mfma_f32_16x16x32_bf16 v[96:99], v[178:181], v[210:213], v[96:99]
	v_mfma_f32_16x16x32_bf16 v[88:91], v[186:189], v[210:213], v[88:91]
	v_mfma_f32_16x16x32_bf16 v[80:83], v[178:181], v[218:221], v[80:83]
	v_mfma_f32_16x16x32_bf16 v[72:75], v[186:189], v[218:221], v[72:75]
	v_mfma_f32_16x16x32_bf16 v[68:71], v[178:181], v[226:229], v[68:71]
	v_mfma_f32_16x16x32_bf16 v[64:67], v[186:189], v[226:229], v[64:67]
	v_mfma_f32_16x16x32_bf16 v[116:119], v[182:185], v[202:205], v[116:119]
	v_mfma_f32_16x16x32_bf16 v[108:111], v[190:193], v[202:205], v[108:111]
	v_mfma_f32_16x16x32_bf16 v[96:99], v[182:185], v[214:217], v[96:99]
	v_mfma_f32_16x16x32_bf16 v[88:91], v[190:193], v[214:217], v[88:91]
	v_mfma_f32_16x16x32_bf16 v[80:83], v[182:185], v[222:225], v[80:83]
	v_mfma_f32_16x16x32_bf16 v[72:75], v[190:193], v[222:225], v[72:75]
	v_mfma_f32_16x16x32_bf16 v[68:71], v[182:185], v[230:233], v[68:71]
	v_mfma_f32_16x16x32_bf16 v[64:67], v[190:193], v[230:233], v[64:67]
	s_setprio 0
	s_barrier
	s_add_i32 s7, s7, s13
	v_lshl_add_u64 v[198:199], v[198:199], 0, s[66:67]
	s_mov_b32 m0, s7
	ds_read_b128 v[194:197], v174 offset:49152
	ds_read_b128 v[202:205], v174 offset:50176
	ds_read_b128 v[210:213], v174 offset:51200
	ds_read_b128 v[214:217], v174 offset:52224
	ds_read_b128 v[218:221], v174 offset:53248
	ds_read_b128 v[222:225], v174 offset:54272
	ds_read_b128 v[226:229], v174 offset:55296
	ds_read_b128 v[230:233], v174 offset:56320
	global_load_lds_dwordx4 v[198:199], off
	s_add_i32 m0, s7, 0x2000
	s_add_u32 s24, s82, 0x40080
	v_lshl_add_u64 v[198:199], v[206:207], 0, s[66:67]
	s_addc_u32 s25, s83, 0
	s_add_i32 s7, s86, s13
	global_load_lds_dwordx4 v[198:199], off
	v_lshl_add_u64 v[198:199], s[24:25], 0, v[132:133]
	s_mov_b32 m0, s7
	s_nop 0
	global_load_lds_dwordx4 v[198:199], off
	v_lshl_add_u64 v[198:199], s[24:25], 0, v[136:137]
	s_add_i32 m0, s7, 0x2000
	s_nop 0
	global_load_lds_dwordx4 v[198:199], off
	v_lshl_add_u64 v[198:199], v[234:235], 0, s[66:67]
	s_mov_b32 m0, s90
	s_nop 0
	global_load_lds_dwordx4 v[198:199], off
	v_lshl_add_u64 v[198:199], v[236:237], 0, s[66:67]
	s_mov_b32 m0, s91
	s_nop 0
	global_load_lds_dwordx4 v[198:199], off
	s_waitcnt vmcnt(6)
	s_waitcnt lgkmcnt(0)
	s_barrier
	s_setprio 1
	s_waitcnt lgkmcnt(0)
	v_mfma_f32_16x16x32_bf16 v[60:63], v[148:151], v[194:197], v[60:63]
	v_mfma_f32_16x16x32_bf16 v[56:59], v[156:159], v[194:197], v[56:59]
	v_mfma_f32_16x16x32_bf16 v[52:55], v[148:151], v[210:213], v[52:55]
	v_mfma_f32_16x16x32_bf16 v[44:47], v[156:159], v[210:213], v[44:47]
	v_mfma_f32_16x16x32_bf16 v[36:39], v[148:151], v[218:221], v[36:39]
	v_mfma_f32_16x16x32_bf16 v[28:31], v[156:159], v[218:221], v[28:31]
	v_mfma_f32_16x16x32_bf16 v[20:23], v[148:151], v[226:229], v[20:23]
	v_mfma_f32_16x16x32_bf16 v[12:15], v[156:159], v[226:229], v[12:15]
	v_mfma_f32_16x16x32_bf16 v[60:63], v[152:155], v[202:205], v[60:63]
	v_mfma_f32_16x16x32_bf16 v[56:59], v[160:163], v[202:205], v[56:59]
	v_mfma_f32_16x16x32_bf16 v[52:55], v[152:155], v[214:217], v[52:55]
	v_mfma_f32_16x16x32_bf16 v[44:47], v[160:163], v[214:217], v[44:47]
	v_mfma_f32_16x16x32_bf16 v[36:39], v[152:155], v[222:225], v[36:39]
	v_mfma_f32_16x16x32_bf16 v[28:31], v[160:163], v[222:225], v[28:31]
	v_mfma_f32_16x16x32_bf16 v[20:23], v[152:155], v[230:233], v[20:23]
	v_mfma_f32_16x16x32_bf16 v[12:15], v[160:163], v[230:233], v[12:15]
	s_setprio 0
	s_setprio 1
	v_mfma_f32_16x16x32_bf16 v[48:51], v[178:181], v[194:197], v[48:51]
	v_mfma_f32_16x16x32_bf16 v[40:43], v[186:189], v[194:197], v[40:43]
	v_mfma_f32_16x16x32_bf16 v[32:35], v[178:181], v[210:213], v[32:35]
	v_mfma_f32_16x16x32_bf16 v[24:27], v[186:189], v[210:213], v[24:27]
	v_mfma_f32_16x16x32_bf16 v[16:19], v[178:181], v[218:221], v[16:19]
	v_mfma_f32_16x16x32_bf16 v[8:11], v[186:189], v[218:221], v[8:11]
	v_mfma_f32_16x16x32_bf16 v[4:7], v[178:181], v[226:229], v[4:7]
	v_mfma_f32_16x16x32_bf16 v[0:3], v[186:189], v[226:229], v[0:3]
	v_mfma_f32_16x16x32_bf16 v[48:51], v[182:185], v[202:205], v[48:51]
	v_mfma_f32_16x16x32_bf16 v[40:43], v[190:193], v[202:205], v[40:43]
	v_mfma_f32_16x16x32_bf16 v[32:35], v[182:185], v[214:217], v[32:35]
	v_mfma_f32_16x16x32_bf16 v[24:27], v[190:193], v[214:217], v[24:27]
	v_mfma_f32_16x16x32_bf16 v[16:19], v[182:185], v[222:225], v[16:19]
	v_mfma_f32_16x16x32_bf16 v[8:11], v[190:193], v[222:225], v[8:11]
	v_mfma_f32_16x16x32_bf16 v[4:7], v[182:185], v[230:233], v[4:7]
	v_mfma_f32_16x16x32_bf16 v[0:3], v[190:193], v[230:233], v[0:3]
	s_setprio 0
	s_barrier
	s_add_i32 s6, s6, 2
	s_add_u32 s80, s80, 0x100
	s_addc_u32 s81, s81, 0
	s_add_u32 vcc_hi, vcc_hi, 0x100
	s_addc_u32 s33, s33, 0
	s_cmp_gt_u32 s6, 13
	s_cbranch_scc0 .LBB0_173
	s_and_b64 vcc, exec, s[70:71]
	s_cbranch_vccnz .LBB0_178
	v_lshl_add_u32 v148, s0, 8, v168
	s_cmp_gt_i32 s68, 3
	s_mov_b64 s[0:1], -1
	s_cbranch_scc1 .LBB0_179

.LBB0_241:
	ds_read_b128 v[154:157], v151
	ds_read_b128 v[158:161], v151 offset:1024
	ds_read_b128 v[168:171], v151 offset:2048
	ds_read_b128 v[172:175], v151 offset:3072
	ds_read_b128 v[178:181], v152
	ds_read_b128 v[182:185], v152 offset:1024
	ds_read_b128 v[186:189], v152 offset:2048
	ds_read_b128 v[190:193], v152 offset:3072
	s_add_u32 s24, s76, 0xfffc0080
	s_addc_u32 s25, s77, -1
	s_cmp_eq_u32 s86, 12
	s_cselect_b32 s81, s69, s25
	s_cselect_b32 s80, s75, s24
	s_cselect_b32 s79, s67, s33
	s_cselect_b32 s78, vcc_lo, vcc_hi
	v_lshl_add_u64 v[162:163], s[76:77], 0, v[140:141]
	s_add_i32 m0, s84, 0xc000
	ds_read_b128 v[194:197], v153
	ds_read_b128 v[202:205], v153 offset:1024
	ds_read_b128 v[210:213], v153 offset:2048
	ds_read_b128 v[214:217], v153 offset:3072
	ds_read_b128 v[218:221], v153 offset:4096
	ds_read_b128 v[222:225], v153 offset:5120
	ds_read_b128 v[226:229], v153 offset:6144
	ds_read_b128 v[230:233], v153 offset:7168
	global_load_lds_dwordx4 v[162:163], off
	v_lshl_add_u64 v[162:163], s[76:77], 0, v[142:143]
	s_add_i32 m0, s84, 0xe000
	s_nop 0
	global_load_lds_dwordx4 v[162:163], off
	s_waitcnt vmcnt(8)
	s_waitcnt lgkmcnt(0)
	s_barrier
	s_setprio 1
	s_waitcnt lgkmcnt(0)
	v_mfma_f32_16x16x32_bf16 v[124:127], v[154:157], v[194:197], v[124:127]
	v_mfma_f32_16x16x32_bf16 v[120:123], v[168:171], v[194:197], v[120:123]
	v_mfma_f32_16x16x32_bf16 v[112:115], v[154:157], v[210:213], v[112:115]
	v_mfma_f32_16x16x32_bf16 v[104:107], v[168:171], v[210:213], v[104:107]
	v_mfma_f32_16x16x32_bf16 v[100:103], v[154:157], v[218:221], v[100:103]
	v_mfma_f32_16x16x32_bf16 v[92:95], v[168:171], v[218:221], v[92:95]
	v_mfma_f32_16x16x32_bf16 v[84:87], v[154:157], v[226:229], v[84:87]
	v_mfma_f32_16x16x32_bf16 v[76:79], v[168:171], v[226:229], v[76:79]
	v_mfma_f32_16x16x32_bf16 v[124:127], v[158:161], v[202:205], v[124:127]
	v_mfma_f32_16x16x32_bf16 v[120:123], v[172:175], v[202:205], v[120:123]
	v_mfma_f32_16x16x32_bf16 v[112:115], v[158:161], v[214:217], v[112:115]
	v_mfma_f32_16x16x32_bf16 v[104:107], v[172:175], v[214:217], v[104:107]
	v_mfma_f32_16x16x32_bf16 v[100:103], v[158:161], v[222:225], v[100:103]
	v_mfma_f32_16x16x32_bf16 v[92:95], v[172:175], v[222:225], v[92:95]
	v_mfma_f32_16x16x32_bf16 v[84:87], v[158:161], v[230:233], v[84:87]
	v_mfma_f32_16x16x32_bf16 v[76:79], v[172:175], v[230:233], v[76:79]
	s_setprio 0
	s_setprio 1
	v_mfma_f32_16x16x32_bf16 v[116:119], v[178:181], v[194:197], v[116:119]
	v_mfma_f32_16x16x32_bf16 v[108:111], v[186:189], v[194:197], v[108:111]
	v_mfma_f32_16x16x32_bf16 v[96:99], v[178:181], v[210:213], v[96:99]
	v_mfma_f32_16x16x32_bf16 v[88:91], v[186:189], v[210:213], v[88:91]
	v_mfma_f32_16x16x32_bf16 v[80:83], v[178:181], v[218:221], v[80:83]
	v_mfma_f32_16x16x32_bf16 v[72:75], v[186:189], v[218:221], v[72:75]
	v_mfma_f32_16x16x32_bf16 v[68:71], v[178:181], v[226:229], v[68:71]
	v_mfma_f32_16x16x32_bf16 v[64:67], v[186:189], v[226:229], v[64:67]
	v_mfma_f32_16x16x32_bf16 v[116:119], v[182:185], v[202:205], v[116:119]
	v_mfma_f32_16x16x32_bf16 v[108:111], v[190:193], v[202:205], v[108:111]
	v_mfma_f32_16x16x32_bf16 v[96:99], v[182:185], v[214:217], v[96:99]
	v_mfma_f32_16x16x32_bf16 v[88:91], v[190:193], v[214:217], v[88:91]
	v_mfma_f32_16x16x32_bf16 v[80:83], v[182:185], v[222:225], v[80:83]
	v_mfma_f32_16x16x32_bf16 v[72:75], v[190:193], v[222:225], v[72:75]
	v_mfma_f32_16x16x32_bf16 v[68:71], v[182:185], v[230:233], v[68:71]
	v_mfma_f32_16x16x32_bf16 v[64:67], v[190:193], v[230:233], v[64:67]
	s_setprio 0
	s_barrier
	s_add_i32 s24, s94, s83
	v_lshl_add_u64 v[162:163], s[78:79], 0, v[132:133]
	s_mov_b32 m0, s24
	ds_read_b128 v[194:197], v153 offset:16384
	ds_read_b128 v[202:205], v153 offset:17408
	ds_read_b128 v[210:213], v153 offset:18432
	ds_read_b128 v[214:217], v153 offset:19456
	ds_read_b128 v[218:221], v153 offset:20480
	ds_read_b128 v[222:225], v153 offset:21504
	ds_read_b128 v[226:229], v153 offset:22528
	ds_read_b128 v[230:233], v153 offset:23552
	global_load_lds_dwordx4 v[162:163], off
	s_add_i32 m0, s24, 0x2000
	s_add_u32 s24, s78, 0x40000
	v_lshl_add_u64 v[198:199], s[78:79], 0, v[136:137]
	s_addc_u32 s25, s79, 0
	s_add_i32 s52, s95, s83
	global_load_lds_dwordx4 v[198:199], off
	v_lshl_add_u64 v[206:207], s[24:25], 0, v[132:133]
	s_mov_b32 m0, s52
	v_lshl_add_u64 v[234:235], s[80:81], 0, v[134:135]
	global_load_lds_dwordx4 v[206:207], off
	v_lshl_add_u64 v[206:207], s[24:25], 0, v[136:137]
	s_add_i32 m0, s52, 0x2000
	s_nop 0
	global_load_lds_dwordx4 v[206:207], off
	s_waitcnt vmcnt(6)
	s_waitcnt lgkmcnt(0)
	s_barrier
	s_setprio 1
	s_waitcnt lgkmcnt(0)
	v_mfma_f32_16x16x32_bf16 v[60:63], v[154:157], v[194:197], v[60:63]
	v_mfma_f32_16x16x32_bf16 v[56:59], v[168:171], v[194:197], v[56:59]
	v_mfma_f32_16x16x32_bf16 v[52:55], v[154:157], v[210:213], v[52:55]
	v_mfma_f32_16x16x32_bf16 v[44:47], v[168:171], v[210:213], v[44:47]
	v_mfma_f32_16x16x32_bf16 v[36:39], v[154:157], v[218:221], v[36:39]
	v_mfma_f32_16x16x32_bf16 v[28:31], v[168:171], v[218:221], v[28:31]
	v_mfma_f32_16x16x32_bf16 v[20:23], v[154:157], v[226:229], v[20:23]
	v_mfma_f32_16x16x32_bf16 v[12:15], v[168:171], v[226:229], v[12:15]
	v_mfma_f32_16x16x32_bf16 v[60:63], v[158:161], v[202:205], v[60:63]
	v_mfma_f32_16x16x32_bf16 v[56:59], v[172:175], v[202:205], v[56:59]
	v_mfma_f32_16x16x32_bf16 v[52:55], v[158:161], v[214:217], v[52:55]
	v_mfma_f32_16x16x32_bf16 v[44:47], v[172:175], v[214:217], v[44:47]
	v_mfma_f32_16x16x32_bf16 v[36:39], v[158:161], v[222:225], v[36:39]
	v_mfma_f32_16x16x32_bf16 v[28:31], v[172:175], v[222:225], v[28:31]
	v_mfma_f32_16x16x32_bf16 v[20:23], v[158:161], v[230:233], v[20:23]
	v_mfma_f32_16x16x32_bf16 v[12:15], v[172:175], v[230:233], v[12:15]
	s_setprio 0
	s_setprio 1
	v_mfma_f32_16x16x32_bf16 v[48:51], v[178:181], v[194:197], v[48:51]
	v_mfma_f32_16x16x32_bf16 v[40:43], v[186:189], v[194:197], v[40:43]
	v_mfma_f32_16x16x32_bf16 v[32:35], v[178:181], v[210:213], v[32:35]
	v_mfma_f32_16x16x32_bf16 v[24:27], v[186:189], v[210:213], v[24:27]
	v_mfma_f32_16x16x32_bf16 v[16:19], v[178:181], v[218:221], v[16:19]
	v_mfma_f32_16x16x32_bf16 v[8:11], v[186:189], v[218:221], v[8:11]
	v_mfma_f32_16x16x32_bf16 v[4:7], v[178:181], v[226:229], v[4:7]
	v_mfma_f32_16x16x32_bf16 v[0:3], v[186:189], v[226:229], v[0:3]
	v_mfma_f32_16x16x32_bf16 v[48:51], v[182:185], v[202:205], v[48:51]
	v_mfma_f32_16x16x32_bf16 v[40:43], v[190:193], v[202:205], v[40:43]
	v_mfma_f32_16x16x32_bf16 v[32:35], v[182:185], v[214:217], v[32:35]
	v_mfma_f32_16x16x32_bf16 v[24:27], v[190:193], v[214:217], v[24:27]
	v_mfma_f32_16x16x32_bf16 v[16:19], v[182:185], v[222:225], v[16:19]
	v_mfma_f32_16x16x32_bf16 v[8:11], v[190:193], v[222:225], v[8:11]
	v_mfma_f32_16x16x32_bf16 v[4:7], v[182:185], v[230:233], v[4:7]
	v_mfma_f32_16x16x32_bf16 v[0:3], v[190:193], v[230:233], v[0:3]
	s_setprio 0
	s_barrier
	s_add_i32 s52, 0, 0x18000
	v_add_u32_e32 v138, s52, v149
	s_add_i32 s53, 0, 0x1c000
	ds_read_b128 v[154:157], v138
	ds_read_b128 v[158:161], v138 offset:1024
	ds_read_b128 v[168:171], v138 offset:2048
	ds_read_b128 v[172:175], v138 offset:3072
	v_add_u32_e32 v138, s53, v149
	ds_read_b128 v[178:181], v138
	ds_read_b128 v[182:185], v138 offset:1024
	ds_read_b128 v[186:189], v138 offset:2048
	ds_read_b128 v[190:193], v138 offset:3072
	v_lshl_add_u64 v[206:207], s[80:81], 0, v[130:131]
	s_mov_b32 m0, s84
	s_nop 0
	global_load_lds_dwordx4 v[206:207], off
	s_mov_b32 m0, s85
	s_nop 0
	global_load_lds_dwordx4 v[234:235], off
	s_add_u32 s24, s80, 0x40000
	s_addc_u32 s25, s81, 0
	s_mov_b32 m0, s87
	v_lshl_add_u64 v[236:237], s[24:25], 0, v[130:131]
	ds_read_b128 v[194:197], v153 offset:32768
	ds_read_b128 v[202:205], v153 offset:33792
	ds_read_b128 v[210:213], v153 offset:34816
	ds_read_b128 v[214:217], v153 offset:35840
	ds_read_b128 v[218:221], v153 offset:36864
	ds_read_b128 v[222:225], v153 offset:37888
	ds_read_b128 v[226:229], v153 offset:38912
	ds_read_b128 v[230:233], v153 offset:39936
	global_load_lds_dwordx4 v[236:237], off
	v_lshl_add_u64 v[236:237], s[24:25], 0, v[134:135]
	s_mov_b32 m0, s88
	s_nop 0
	global_load_lds_dwordx4 v[236:237], off
	s_waitcnt vmcnt(8)
	s_waitcnt lgkmcnt(0)
	s_barrier
	s_setprio 1
	s_waitcnt lgkmcnt(0)
	v_mfma_f32_16x16x32_bf16 v[124:127], v[154:157], v[194:197], v[124:127]
	v_mfma_f32_16x16x32_bf16 v[120:123], v[168:171], v[194:197], v[120:123]
	v_mfma_f32_16x16x32_bf16 v[112:115], v[154:157], v[210:213], v[112:115]
	v_mfma_f32_16x16x32_bf16 v[104:107], v[168:171], v[210:213], v[104:107]
	v_mfma_f32_16x16x32_bf16 v[100:103], v[154:157], v[218:221], v[100:103]
	v_mfma_f32_16x16x32_bf16 v[92:95], v[168:171], v[218:221], v[92:95]
	v_mfma_f32_16x16x32_bf16 v[84:87], v[154:157], v[226:229], v[84:87]
	v_mfma_f32_16x16x32_bf16 v[76:79], v[168:171], v[226:229], v[76:79]
	v_mfma_f32_16x16x32_bf16 v[124:127], v[158:161], v[202:205], v[124:127]
	v_mfma_f32_16x16x32_bf16 v[120:123], v[172:175], v[202:205], v[120:123]
	v_mfma_f32_16x16x32_bf16 v[112:115], v[158:161], v[214:217], v[112:115]
	v_mfma_f32_16x16x32_bf16 v[104:107], v[172:175], v[214:217], v[104:107]
	v_mfma_f32_16x16x32_bf16 v[100:103], v[158:161], v[222:225], v[100:103]
	v_mfma_f32_16x16x32_bf16 v[92:95], v[172:175], v[222:225], v[92:95]
	v_mfma_f32_16x16x32_bf16 v[84:87], v[158:161], v[230:233], v[84:87]
	v_mfma_f32_16x16x32_bf16 v[76:79], v[172:175], v[230:233], v[76:79]
	s_setprio 0
	s_setprio 1
	v_mfma_f32_16x16x32_bf16 v[116:119], v[178:181], v[194:197], v[116:119]
	v_mfma_f32_16x16x32_bf16 v[108:111], v[186:189], v[194:197], v[108:111]
	v_mfma_f32_16x16x32_bf16 v[96:99], v[178:181], v[210:213], v[96:99]
	v_mfma_f32_16x16x32_bf16 v[88:91], v[186:189], v[210:213], v[88:91]
	v_mfma_f32_16x16x32_bf16 v[80:83], v[178:181], v[218:221], v[80:83]
	v_mfma_f32_16x16x32_bf16 v[72:75], v[186:189], v[218:221], v[72:75]
	v_mfma_f32_16x16x32_bf16 v[68:71], v[178:181], v[226:229], v[68:71]
	v_mfma_f32_16x16x32_bf16 v[64:67], v[186:189], v[226:229], v[64:67]
	v_mfma_f32_16x16x32_bf16 v[116:119], v[182:185], v[202:205], v[116:119]
	v_mfma_f32_16x16x32_bf16 v[108:111], v[190:193], v[202:205], v[108:111]
	v_mfma_f32_16x16x32_bf16 v[96:99], v[182:185], v[214:217], v[96:99]
	v_mfma_f32_16x16x32_bf16 v[88:91], v[190:193], v[214:217], v[88:91]
	v_mfma_f32_16x16x32_bf16 v[80:83], v[182:185], v[222:225], v[80:83]
	v_mfma_f32_16x16x32_bf16 v[72:75], v[190:193], v[222:225], v[72:75]
	v_mfma_f32_16x16x32_bf16 v[68:71], v[182:185], v[230:233], v[68:71]
	v_mfma_f32_16x16x32_bf16 v[64:67], v[190:193], v[230:233], v[64:67]
	s_setprio 0
	s_barrier
	s_add_i32 s24, s52, s83
	v_lshl_add_u64 v[162:163], v[162:163], 0, s[26:27]
	s_mov_b32 m0, s24
	ds_read_b128 v[194:197], v153 offset:49152
	ds_read_b128 v[202:205], v153 offset:50176
	ds_read_b128 v[210:213], v153 offset:51200
	ds_read_b128 v[214:217], v153 offset:52224
	ds_read_b128 v[218:221], v153 offset:53248
	ds_read_b128 v[222:225], v153 offset:54272
	ds_read_b128 v[226:229], v153 offset:55296
	ds_read_b128 v[230:233], v153 offset:56320
	global_load_lds_dwordx4 v[162:163], off
	s_add_i32 m0, s24, 0x2000
	s_add_u32 s24, s78, 0x40080
	v_lshl_add_u64 v[162:163], v[198:199], 0, s[26:27]
	s_addc_u32 s25, s79, 0
	s_add_i32 s52, s53, s83
	global_load_lds_dwordx4 v[162:163], off
	v_lshl_add_u64 v[162:163], s[24:25], 0, v[132:133]
	s_mov_b32 m0, s52
	s_nop 0
	global_load_lds_dwordx4 v[162:163], off
	v_lshl_add_u64 v[162:163], s[24:25], 0, v[136:137]
	s_add_i32 m0, s52, 0x2000
	s_nop 0
	global_load_lds_dwordx4 v[162:163], off
	v_lshl_add_u64 v[162:163], v[206:207], 0, s[26:27]
	s_mov_b32 m0, s90
	s_nop 0
	global_load_lds_dwordx4 v[162:163], off
	v_lshl_add_u64 v[162:163], v[234:235], 0, s[26:27]
	s_mov_b32 m0, s91
	s_nop 0
	global_load_lds_dwordx4 v[162:163], off
	s_waitcnt vmcnt(6)
	s_waitcnt lgkmcnt(0)
	s_barrier
	s_setprio 1
	s_waitcnt lgkmcnt(0)
	v_mfma_f32_16x16x32_bf16 v[60:63], v[154:157], v[194:197], v[60:63]
	v_mfma_f32_16x16x32_bf16 v[56:59], v[168:171], v[194:197], v[56:59]
	v_mfma_f32_16x16x32_bf16 v[52:55], v[154:157], v[210:213], v[52:55]
	v_mfma_f32_16x16x32_bf16 v[44:47], v[168:171], v[210:213], v[44:47]
	v_mfma_f32_16x16x32_bf16 v[36:39], v[154:157], v[218:221], v[36:39]
	v_mfma_f32_16x16x32_bf16 v[28:31], v[168:171], v[218:221], v[28:31]
	v_mfma_f32_16x16x32_bf16 v[20:23], v[154:157], v[226:229], v[20:23]
	v_mfma_f32_16x16x32_bf16 v[12:15], v[168:171], v[226:229], v[12:15]
	v_mfma_f32_16x16x32_bf16 v[60:63], v[158:161], v[202:205], v[60:63]
	v_mfma_f32_16x16x32_bf16 v[56:59], v[172:175], v[202:205], v[56:59]
	v_mfma_f32_16x16x32_bf16 v[52:55], v[158:161], v[214:217], v[52:55]
	v_mfma_f32_16x16x32_bf16 v[44:47], v[172:175], v[214:217], v[44:47]
	v_mfma_f32_16x16x32_bf16 v[36:39], v[158:161], v[222:225], v[36:39]
	v_mfma_f32_16x16x32_bf16 v[28:31], v[172:175], v[222:225], v[28:31]
	v_mfma_f32_16x16x32_bf16 v[20:23], v[158:161], v[230:233], v[20:23]
	v_mfma_f32_16x16x32_bf16 v[12:15], v[172:175], v[230:233], v[12:15]
	s_setprio 0
	s_setprio 1
	v_mfma_f32_16x16x32_bf16 v[48:51], v[178:181], v[194:197], v[48:51]
	v_mfma_f32_16x16x32_bf16 v[40:43], v[186:189], v[194:197], v[40:43]
	v_mfma_f32_16x16x32_bf16 v[32:35], v[178:181], v[210:213], v[32:35]
	v_mfma_f32_16x16x32_bf16 v[24:27], v[186:189], v[210:213], v[24:27]
	v_mfma_f32_16x16x32_bf16 v[16:19], v[178:181], v[218:221], v[16:19]
	v_mfma_f32_16x16x32_bf16 v[8:11], v[186:189], v[218:221], v[8:11]
	v_mfma_f32_16x16x32_bf16 v[4:7], v[178:181], v[226:229], v[4:7]
	v_mfma_f32_16x16x32_bf16 v[0:3], v[186:189], v[226:229], v[0:3]
	v_mfma_f32_16x16x32_bf16 v[48:51], v[182:185], v[202:205], v[48:51]
	v_mfma_f32_16x16x32_bf16 v[40:43], v[190:193], v[202:205], v[40:43]
	v_mfma_f32_16x16x32_bf16 v[32:35], v[182:185], v[214:217], v[32:35]
	v_mfma_f32_16x16x32_bf16 v[24:27], v[190:193], v[214:217], v[24:27]
	v_mfma_f32_16x16x32_bf16 v[16:19], v[182:185], v[222:225], v[16:19]
	v_mfma_f32_16x16x32_bf16 v[8:11], v[190:193], v[222:225], v[8:11]
	v_mfma_f32_16x16x32_bf16 v[4:7], v[182:185], v[230:233], v[4:7]
	v_mfma_f32_16x16x32_bf16 v[0:3], v[190:193], v[230:233], v[0:3]
	s_setprio 0
	s_barrier
	s_add_i32 s86, s86, 2
	s_add_u32 s76, s76, 0x100
	s_addc_u32 s77, s77, 0
	s_add_u32 vcc_hi, vcc_hi, 0x100
	s_addc_u32 s33, s33, 0
	s_cmp_gt_u32 s86, 13
	s_cbranch_scc0 .LBB0_241
	s_and_b64 vcc, exec, s[34:35]
	s_cbranch_vccz .LBB0_244
	s_barrier

.Lan_327:
	s_and_b32 s88, s90, 1
	s_mul_i32 s33, s88, 0x4400
	v_add_u32_e32 v235, s33, v230
	s_add_i32 s87, s90, 1
	s_and_b32 s89, s87, 1
	s_mul_i32 s33, s89, 0x4800
	v_add_u32_e32 v234, s33, v215
	ds_read_b128 v[64:67], v235
	ds_read_b128 v[68:71], v235 offset:32
	ds_read_b128 v[72:75], v235 offset:64
	ds_read_b128 v[76:79], v235 offset:96
	ds_read_b128 v[160:163], v234 offset:34816
	s_cmp_lt_i32 s87, s38
	s_cselect_b64 s[54:55], -1, 0
	s_cmp_ge_i32 s87, s38
	s_cbranch_scc1 .Lan_329
	v_lshl_add_u64 v[244:245], s[62:63], 0, v[206:207]
	v_add_co_u32_e32 v246, vcc, 0x8f61000, v244
	s_nop 1
	v_addc_co_u32_e32 v247, vcc, 0, v245, vcc
	v_add_co_u32_e32 v244, vcc, 0x8f89000, v244
	s_nop 1
	v_addc_co_u32_e32 v245, vcc, 0, v245, vcc
	global_load_dwordx4 v[128:131], v[246:247], off
	global_load_dwordx4 v[132:135], v[244:245], off

.Lpr_t0_done:
	s_waitcnt lgkmcnt(4)
	v_mfma_f32_32x32x16_bf16 v[96:111], v[64:67], v[112:115], v[96:111]
	ds_read_b128 v[244:247], v234 offset:34848
	v_exp_f32_e32 v80, v80
	v_exp_f32_e32 v81, v81
	v_add_f32_e32 v238, 0, v80
	v_add_f32_e32 v238, v238, v81
	s_waitcnt lgkmcnt(4)
	v_mfma_f32_32x32x16_bf16 v[96:111], v[68:71], v[116:119], v[96:111]
	ds_read_b128 v[64:67], v234 offset:39424
	v_exp_f32_e32 v82, v82
	v_exp_f32_e32 v83, v83
	v_add_f32_e32 v238, v238, v82
	v_add_f32_e32 v238, v238, v83
	s_waitcnt lgkmcnt(4)
	v_mfma_f32_32x32x16_bf16 v[96:111], v[72:75], v[120:123], v[96:111]
	ds_read_b128 v[68:71], v234 offset:39456
	v_exp_f32_e32 v84, v84
	v_exp_f32_e32 v85, v85
	v_add_f32_e32 v238, v238, v84
	v_add_f32_e32 v238, v238, v85
	s_waitcnt lgkmcnt(4)
	v_mfma_f32_32x32x16_bf16 v[96:111], v[76:79], v[124:127], v[96:111]
	ds_read_b128 v[72:75], v234 offset:44032
	v_exp_f32_e32 v86, v86
	v_exp_f32_e32 v87, v87
	v_add_f32_e32 v238, v238, v86
	v_add_f32_e32 v238, v238, v87
	s_waitcnt lgkmcnt(4)
	v_mfma_f32_32x32x16_bf16 v[48:63], v[160:163], v[144:147], v[48:63]
	ds_read_b128 v[76:79], v234 offset:44064
	v_cvt_pk_bf16_f32 v152, v80, v81
	v_cvt_pk_bf16_f32 v153, v82, v83
	v_cvt_pk_bf16_f32 v154, v84, v85
	v_cvt_pk_bf16_f32 v155, v86, v87
	v_add_f32_e32 v255, 0x42800000, v237
	v_fma_f32 v254, v236, v255, v253
	s_waitcnt lgkmcnt(4)
	v_mfma_f32_32x32x16_bf16 v[48:63], v[244:247], v[148:151], v[48:63]
	ds_read_b128 v[160:163], v234 offset:48640
	v_exp_f32_e32 v88, v88
	v_exp_f32_e32 v89, v89
	v_add_f32_e32 v238, v238, v88
	v_add_f32_e32 v238, v238, v89
	v_fmamk_f32 v80, v201, 0x42000000, v254
	v_fmamk_f32 v81, v201, 0x42040000, v254
	s_waitcnt lgkmcnt(4)
	v_mfma_f32_32x32x16_bf16 v[32:47], v[64:67], v[144:147], v[32:47]
	ds_read_b128 v[244:247], v234 offset:48672
	v_exp_f32_e32 v90, v90
	v_exp_f32_e32 v91, v91
	v_add_f32_e32 v238, v238, v90
	v_add_f32_e32 v238, v238, v91
	v_fmamk_f32 v82, v201, 0x42080000, v254
	v_fmamk_f32 v83, v201, 0x420c0000, v254
	s_waitcnt lgkmcnt(4)
	v_mfma_f32_32x32x16_bf16 v[32:47], v[68:71], v[148:151], v[32:47]
	ds_read_b128 v[64:67], v235 offset:8704
	v_exp_f32_e32 v92, v92
	v_exp_f32_e32 v93, v93
	v_add_f32_e32 v238, v238, v92
	v_add_f32_e32 v238, v238, v93
	v_fmamk_f32 v84, v201, 0x42100000, v254
	v_fmamk_f32 v85, v201, 0x42140000, v254
	s_waitcnt lgkmcnt(4)
	v_mfma_f32_32x32x16_bf16 v[16:31], v[72:75], v[144:147], v[16:31]
	ds_read_b128 v[68:71], v235 offset:8736
	v_exp_f32_e32 v94, v94
	v_exp_f32_e32 v95, v95
	v_add_f32_e32 v238, v238, v94
	v_add_f32_e32 v238, v238, v95
	v_fmamk_f32 v86, v201, 0x42180000, v254
	v_fmamk_f32 v87, v201, 0x421c0000, v254
	s_waitcnt lgkmcnt(4)
	v_mfma_f32_32x32x16_bf16 v[16:31], v[76:79], v[148:151], v[16:31]
	ds_read_b128 v[72:75], v235 offset:8768
	v_cvt_pk_bf16_f32 v156, v88, v89
	v_cvt_pk_bf16_f32 v157, v90, v91
	v_cvt_pk_bf16_f32 v158, v92, v93
	v_cvt_pk_bf16_f32 v159, v94, v95
	s_waitcnt lgkmcnt(4)
	v_mfma_f32_32x32x16_bf16 v[0:15], v[160:163], v[144:147], v[0:15]
	ds_read_b128 v[76:79], v235 offset:8800
	v_fmamk_f32 v88, v201, 0x42400000, v254
	v_fmamk_f32 v89, v201, 0x42440000, v254
	v_fmamk_f32 v90, v201, 0x42480000, v254
	v_fmamk_f32 v91, v201, 0x424c0000, v254
	v_add_f32_e32 v238, v238, v233
	s_waitcnt lgkmcnt(4)
	v_mfma_f32_32x32x16_bf16 v[0:15], v[244:247], v[148:151], v[0:15]
	ds_read_b128 v[160:163], v234 offset:34880
	v_fmamk_f32 v92, v201, 0x42500000, v254
	v_fmamk_f32 v93, v201, 0x42540000, v254
	v_fmamk_f32 v94, v201, 0x42580000, v254
	v_fmamk_f32 v95, v201, 0x425c0000, v254
	s_cmp_lt_u32 s90, 2
	s_cbranch_scc1 .LfixA_skip_do
	s_cmp_lt_i32 s90, s38
	s_cbranch_scc1 .LfixA_skip
.LfixA_skip_do:
	v_cmp_ge_u32_e32 vcc, s90, v203
	v_add_f32_e32 v255, 0x42800000, v237
	s_and_b64 vcc, vcc, s[56:57]
	v_cndmask_b32_e32 v208, v229, v255, vcc
	v_add_f32_e32 v255, 0xc2000000, v208
	v_fma_f32 v80, -v201, |v255|, v253
	v_add_f32_e32 v255, 0xc2040000, v208
	v_fma_f32 v81, -v201, |v255|, v253
	v_add_f32_e32 v255, 0xc2080000, v208
	v_fma_f32 v82, -v201, |v255|, v253
	v_add_f32_e32 v255, 0xc20c0000, v208
	v_fma_f32 v83, -v201, |v255|, v253
	v_add_f32_e32 v255, 0xc2100000, v208
	v_fma_f32 v84, -v201, |v255|, v253
	v_add_f32_e32 v255, 0xc2140000, v208
	v_fma_f32 v85, -v201, |v255|, v253
	v_add_f32_e32 v255, 0xc2180000, v208
	v_fma_f32 v86, -v201, |v255|, v253
	v_add_f32_e32 v255, 0xc21c0000, v208
	v_fma_f32 v87, -v201, |v255|, v253
	v_add_f32_e32 v255, 0xc2400000, v208
	v_fma_f32 v88, -v201, |v255|, v253
	v_add_f32_e32 v255, 0xc2440000, v208
	v_fma_f32 v89, -v201, |v255|, v253
	v_add_f32_e32 v255, 0xc2480000, v208
	v_fma_f32 v90, -v201, |v255|, v253
	v_add_f32_e32 v255, 0xc24c0000, v208
	v_fma_f32 v91, -v201, |v255|, v253
	v_add_f32_e32 v255, 0xc2500000, v208
	v_fma_f32 v92, -v201, |v255|, v253
	v_add_f32_e32 v255, 0xc2540000, v208
	v_fma_f32 v93, -v201, |v255|, v253
	v_add_f32_e32 v255, 0xc2580000, v208
	v_fma_f32 v94, -v201, |v255|, v253
	v_add_f32_e32 v255, 0xc25c0000, v208
	v_fma_f32 v95, -v201, |v255|, v253
	s_nop 1

.Lpr_t12_done:
	s_waitcnt lgkmcnt(4)
	v_mfma_f32_32x32x16_bf16 v[80:95], v[64:67], v[112:115], v[80:95]
	ds_read_b128 v[244:247], v234 offset:34912
	v_exp_f32_e32 v96, v96
	v_exp_f32_e32 v97, v97
	v_add_f32_e32 v233, 0, v96
	v_add_f32_e32 v233, v233, v97
	s_waitcnt lgkmcnt(4)
	v_mfma_f32_32x32x16_bf16 v[80:95], v[68:71], v[116:119], v[80:95]
	ds_read_b128 v[64:67], v234 offset:39488
	v_exp_f32_e32 v98, v98
	v_exp_f32_e32 v99, v99
	v_add_f32_e32 v233, v233, v98
	v_add_f32_e32 v233, v233, v99
	s_waitcnt lgkmcnt(4)
	v_mfma_f32_32x32x16_bf16 v[80:95], v[72:75], v[120:123], v[80:95]
	ds_read_b128 v[68:71], v234 offset:39520
	v_exp_f32_e32 v100, v100
	v_exp_f32_e32 v101, v101
	v_add_f32_e32 v233, v233, v100
	v_add_f32_e32 v233, v233, v101
	s_waitcnt lgkmcnt(4)
	v_mfma_f32_32x32x16_bf16 v[80:95], v[76:79], v[124:127], v[80:95]
	ds_read_b128 v[72:75], v234 offset:44096
	v_exp_f32_e32 v102, v102
	v_exp_f32_e32 v103, v103
	v_add_f32_e32 v233, v233, v102
	v_add_f32_e32 v233, v233, v103
	s_waitcnt lgkmcnt(4)
	v_mfma_f32_32x32x16_bf16 v[48:63], v[160:163], v[152:155], v[48:63]
	ds_read_b128 v[76:79], v234 offset:44128
	v_cvt_pk_bf16_f32 v144, v96, v97
	v_cvt_pk_bf16_f32 v145, v98, v99
	v_cvt_pk_bf16_f32 v146, v100, v101
	v_cvt_pk_bf16_f32 v147, v102, v103
	v_add_f32_e32 v255, 0x43000000, v237
	v_fma_f32 v254, v236, v255, v253
	s_waitcnt lgkmcnt(4)
	v_mfma_f32_32x32x16_bf16 v[48:63], v[244:247], v[156:159], v[48:63]
	ds_read_b128 v[160:163], v234 offset:48704
	v_exp_f32_e32 v104, v104
	v_exp_f32_e32 v105, v105
	v_add_f32_e32 v233, v233, v104
	v_add_f32_e32 v233, v233, v105
	v_fmamk_f32 v96, v201, 0x00000000, v254
	v_fmamk_f32 v97, v201, 0x3f800000, v254
	s_waitcnt lgkmcnt(4)
	v_mfma_f32_32x32x16_bf16 v[32:47], v[64:67], v[152:155], v[32:47]
	ds_read_b128 v[244:247], v234 offset:48736
	v_exp_f32_e32 v106, v106
	v_exp_f32_e32 v107, v107
	v_add_f32_e32 v233, v233, v106
	v_add_f32_e32 v233, v233, v107
	v_fmamk_f32 v98, v201, 0x40000000, v254
	v_fmamk_f32 v99, v201, 0x40400000, v254
	s_waitcnt lgkmcnt(4)
	v_mfma_f32_32x32x16_bf16 v[32:47], v[68:71], v[156:159], v[32:47]
	v_exp_f32_e32 v108, v108
	v_exp_f32_e32 v109, v109
	v_add_f32_e32 v233, v233, v108
	v_add_f32_e32 v233, v233, v109
	v_fmamk_f32 v100, v201, 0x40800000, v254
	v_fmamk_f32 v101, v201, 0x40a00000, v254
	s_waitcnt lgkmcnt(3)
	v_mfma_f32_32x32x16_bf16 v[16:31], v[72:75], v[152:155], v[16:31]
	v_exp_f32_e32 v110, v110
	v_exp_f32_e32 v111, v111
	v_add_f32_e32 v233, v233, v110
	v_add_f32_e32 v233, v233, v111
	v_fmamk_f32 v102, v201, 0x40c00000, v254
	v_fmamk_f32 v103, v201, 0x40e00000, v254
	s_waitcnt lgkmcnt(2)
	v_mfma_f32_32x32x16_bf16 v[16:31], v[76:79], v[156:159], v[16:31]
	v_cvt_pk_bf16_f32 v148, v104, v105
	v_cvt_pk_bf16_f32 v149, v106, v107
	v_cvt_pk_bf16_f32 v150, v108, v109
	v_cvt_pk_bf16_f32 v151, v110, v111
	s_waitcnt lgkmcnt(1)
	v_mfma_f32_32x32x16_bf16 v[0:15], v[160:163], v[152:155], v[0:15]
	v_fmamk_f32 v104, v201, 0x41800000, v254
	v_fmamk_f32 v105, v201, 0x41880000, v254
	v_fmamk_f32 v106, v201, 0x41900000, v254
	v_fmamk_f32 v107, v201, 0x41980000, v254
	v_add_f32_e32 v233, v233, v238
	s_waitcnt lgkmcnt(0)
	v_mfma_f32_32x32x16_bf16 v[0:15], v[244:247], v[156:159], v[0:15]
	v_fmamk_f32 v108, v201, 0x41a00000, v254
	v_fmamk_f32 v109, v201, 0x41a80000, v254
	v_fmamk_f32 v110, v201, 0x41b00000, v254
	v_fmamk_f32 v111, v201, 0x41b80000, v254
	s_cmp_lt_u32 s90, 1
	s_cbranch_scc1 .LfixB_skip_do
	s_cmp_lt_i32 s87, s38
	s_cbranch_scc1 .LfixB_skip
.LfixB_skip_do:
	v_cvt_f32_i32_e32 v255, v231
	v_cmp_ge_u32_e32 vcc, s87, v203
	v_add_f32_e32 v255, 0x43000000, v255
	s_and_b64 vcc, vcc, s[54:55]
	v_cndmask_b32_e32 v208, v229, v255, vcc
	v_add_f32_e32 v255, 0x80000000, v208
	v_fma_f32 v96, -v201, |v255|, v253
	v_add_f32_e32 v255, 0xbf800000, v208
	v_fma_f32 v97, -v201, |v255|, v253
	v_add_f32_e32 v255, 0xc0000000, v208
	v_fma_f32 v98, -v201, |v255|, v253
	v_add_f32_e32 v255, 0xc0400000, v208
	v_fma_f32 v99, -v201, |v255|, v253
	v_add_f32_e32 v255, 0xc0800000, v208
	v_fma_f32 v100, -v201, |v255|, v253
	v_add_f32_e32 v255, 0xc0a00000, v208
	v_fma_f32 v101, -v201, |v255|, v253
	v_add_f32_e32 v255, 0xc0c00000, v208
	v_fma_f32 v102, -v201, |v255|, v253
	v_add_f32_e32 v255, 0xc0e00000, v208
	v_fma_f32 v103, -v201, |v255|, v253
	v_add_f32_e32 v255, 0xc1800000, v208
	v_fma_f32 v104, -v201, |v255|, v253
	v_add_f32_e32 v255, 0xc1880000, v208
	v_fma_f32 v105, -v201, |v255|, v253
	v_add_f32_e32 v255, 0xc1900000, v208
	v_fma_f32 v106, -v201, |v255|, v253
	v_add_f32_e32 v255, 0xc1980000, v208
	v_fma_f32 v107, -v201, |v255|, v253
	v_add_f32_e32 v255, 0xc1a00000, v208
	v_fma_f32 v108, -v201, |v255|, v253
	v_add_f32_e32 v255, 0xc1a80000, v208
	v_fma_f32 v109, -v201, |v255|, v253
	v_add_f32_e32 v255, 0xc1b00000, v208
	v_fma_f32 v110, -v201, |v255|, v253
	v_add_f32_e32 v255, 0xc1b80000, v208
	v_fma_f32 v111, -v201, |v255|, v253
	s_nop 1

.LBB0_462:
	v_add_u32_e32 v156, s83, v161
	v_add_u32_e32 v176, s84, v161
	ds_read_b128 v[144:147], v156
	ds_read_b128 v[148:151], v156 offset:1024
	ds_read_b128 v[152:155], v156 offset:2048
	ds_read_b128 v[156:159], v156 offset:3072
	ds_read_b128 v[164:167], v176
	ds_read_b128 v[168:171], v176 offset:1024
	ds_read_b128 v[172:175], v176 offset:2048
	ds_read_b128 v[176:179], v176 offset:3072
	s_add_u32 s58, s70, 0xfffe0080
	s_addc_u32 s59, s71, -1
	s_cmp_eq_u32 s95, 4
	s_cselect_b32 s75, s57, s59
	s_cselect_b32 s74, s91, s58
	s_cselect_b32 s73, s55, s94
	s_cselect_b32 s72, s92, s93
	v_lshl_add_u64 v[216:217], s[70:71], 0, v[136:137]
	s_add_i32 m0, s77, 0xc000
	ds_read_b128 v[180:183], v163
	ds_read_b128 v[184:187], v163 offset:1024
	ds_read_b128 v[188:191], v163 offset:2048
	ds_read_b128 v[192:195], v163 offset:3072
	ds_read_b128 v[196:199], v163 offset:4096
	ds_read_b128 v[200:203], v163 offset:5120
	ds_read_b128 v[204:207], v163 offset:6144
	ds_read_b128 v[212:215], v163 offset:7168
	global_load_lds_dwordx4 v[216:217], off
	v_lshl_add_u64 v[216:217], s[70:71], 0, v[138:139]
	s_add_i32 m0, s77, 0xe000
	s_nop 0
	global_load_lds_dwordx4 v[216:217], off
	s_waitcnt vmcnt(8)
	s_waitcnt lgkmcnt(0)
	s_barrier
	s_setprio 1
	s_waitcnt lgkmcnt(0)
	v_mfma_f32_16x16x32_bf16 v[124:127], v[144:147], v[180:183], v[124:127]
	v_mfma_f32_16x16x32_bf16 v[120:123], v[152:155], v[180:183], v[120:123]
	v_mfma_f32_16x16x32_bf16 v[116:119], v[144:147], v[188:191], v[116:119]
	v_mfma_f32_16x16x32_bf16 v[112:115], v[152:155], v[188:191], v[112:115]
	v_mfma_f32_16x16x32_bf16 v[108:111], v[144:147], v[196:199], v[108:111]
	v_mfma_f32_16x16x32_bf16 v[104:107], v[152:155], v[196:199], v[104:107]
	v_mfma_f32_16x16x32_bf16 v[100:103], v[144:147], v[204:207], v[100:103]
	v_mfma_f32_16x16x32_bf16 v[96:99], v[152:155], v[204:207], v[96:99]
	v_mfma_f32_16x16x32_bf16 v[124:127], v[148:151], v[184:187], v[124:127]
	v_mfma_f32_16x16x32_bf16 v[120:123], v[156:159], v[184:187], v[120:123]
	v_mfma_f32_16x16x32_bf16 v[116:119], v[148:151], v[192:195], v[116:119]
	v_mfma_f32_16x16x32_bf16 v[112:115], v[156:159], v[192:195], v[112:115]
	v_mfma_f32_16x16x32_bf16 v[108:111], v[148:151], v[200:203], v[108:111]
	v_mfma_f32_16x16x32_bf16 v[104:107], v[156:159], v[200:203], v[104:107]
	v_mfma_f32_16x16x32_bf16 v[100:103], v[148:151], v[212:215], v[100:103]
	v_mfma_f32_16x16x32_bf16 v[96:99], v[156:159], v[212:215], v[96:99]
	s_setprio 0
	s_setprio 1
	v_mfma_f32_16x16x32_bf16 v[92:95], v[164:167], v[180:183], v[92:95]
	v_mfma_f32_16x16x32_bf16 v[88:91], v[172:175], v[180:183], v[88:91]
	v_mfma_f32_16x16x32_bf16 v[84:87], v[164:167], v[188:191], v[84:87]
	v_mfma_f32_16x16x32_bf16 v[80:83], v[172:175], v[188:191], v[80:83]
	v_mfma_f32_16x16x32_bf16 v[76:79], v[164:167], v[196:199], v[76:79]
	v_mfma_f32_16x16x32_bf16 v[72:75], v[172:175], v[196:199], v[72:75]
	v_mfma_f32_16x16x32_bf16 v[68:71], v[164:167], v[204:207], v[68:71]
	v_mfma_f32_16x16x32_bf16 v[64:67], v[172:175], v[204:207], v[64:67]
	v_mfma_f32_16x16x32_bf16 v[92:95], v[168:171], v[184:187], v[92:95]
	v_mfma_f32_16x16x32_bf16 v[88:91], v[176:179], v[184:187], v[88:91]
	v_mfma_f32_16x16x32_bf16 v[84:87], v[168:171], v[192:195], v[84:87]
	v_mfma_f32_16x16x32_bf16 v[80:83], v[176:179], v[192:195], v[80:83]
	v_mfma_f32_16x16x32_bf16 v[76:79], v[168:171], v[200:203], v[76:79]
	v_mfma_f32_16x16x32_bf16 v[72:75], v[176:179], v[200:203], v[72:75]
	v_mfma_f32_16x16x32_bf16 v[68:71], v[168:171], v[212:215], v[68:71]
	v_mfma_f32_16x16x32_bf16 v[64:67], v[176:179], v[212:215], v[64:67]
	s_setprio 0
	s_barrier
	s_add_i32 s58, s83, s76
	v_lshl_add_u64 v[216:217], s[72:73], 0, v[130:131]
	s_mov_b32 m0, s58
	ds_read_b128 v[180:183], v163 offset:16384
	ds_read_b128 v[184:187], v163 offset:17408
	ds_read_b128 v[188:191], v163 offset:18432
	ds_read_b128 v[192:195], v163 offset:19456
	ds_read_b128 v[196:199], v163 offset:20480
	ds_read_b128 v[200:203], v163 offset:21504
	ds_read_b128 v[204:207], v163 offset:22528
	ds_read_b128 v[212:215], v163 offset:23552
	global_load_lds_dwordx4 v[216:217], off
	s_add_i32 m0, s58, 0x2000
	s_add_u32 s96, s72, 0x20000
	v_lshl_add_u64 v[218:219], s[72:73], 0, v[134:135]
	s_addc_u32 s97, s73, 0
	s_add_i32 s58, s84, s76
	global_load_lds_dwordx4 v[218:219], off
	v_lshl_add_u64 v[220:221], s[96:97], 0, v[130:131]
	s_mov_b32 m0, s58
	v_lshl_add_u64 v[222:223], s[74:75], 0, v[132:133]
	global_load_lds_dwordx4 v[220:221], off
	v_lshl_add_u64 v[220:221], s[96:97], 0, v[134:135]
	s_add_i32 m0, s58, 0x2000
	s_nop 0
	global_load_lds_dwordx4 v[220:221], off
	s_waitcnt vmcnt(6)
	s_waitcnt lgkmcnt(0)
	s_barrier
	s_setprio 1
	s_waitcnt lgkmcnt(0)
	v_mfma_f32_16x16x32_bf16 v[60:63], v[144:147], v[180:183], v[60:63]
	v_mfma_f32_16x16x32_bf16 v[56:59], v[152:155], v[180:183], v[56:59]
	v_mfma_f32_16x16x32_bf16 v[52:55], v[144:147], v[188:191], v[52:55]
	v_mfma_f32_16x16x32_bf16 v[48:51], v[152:155], v[188:191], v[48:51]
	v_mfma_f32_16x16x32_bf16 v[44:47], v[144:147], v[196:199], v[44:47]
	v_mfma_f32_16x16x32_bf16 v[40:43], v[152:155], v[196:199], v[40:43]
	v_mfma_f32_16x16x32_bf16 v[36:39], v[144:147], v[204:207], v[36:39]
	v_mfma_f32_16x16x32_bf16 v[32:35], v[152:155], v[204:207], v[32:35]
	v_mfma_f32_16x16x32_bf16 v[60:63], v[148:151], v[184:187], v[60:63]
	v_mfma_f32_16x16x32_bf16 v[56:59], v[156:159], v[184:187], v[56:59]
	v_mfma_f32_16x16x32_bf16 v[52:55], v[148:151], v[192:195], v[52:55]
	v_mfma_f32_16x16x32_bf16 v[48:51], v[156:159], v[192:195], v[48:51]
	v_mfma_f32_16x16x32_bf16 v[44:47], v[148:151], v[200:203], v[44:47]
	v_mfma_f32_16x16x32_bf16 v[40:43], v[156:159], v[200:203], v[40:43]
	v_mfma_f32_16x16x32_bf16 v[36:39], v[148:151], v[212:215], v[36:39]
	v_mfma_f32_16x16x32_bf16 v[32:35], v[156:159], v[212:215], v[32:35]
	s_setprio 0
	s_setprio 1
	v_mfma_f32_16x16x32_bf16 v[28:31], v[164:167], v[180:183], v[28:31]
	v_mfma_f32_16x16x32_bf16 v[24:27], v[172:175], v[180:183], v[24:27]
	v_mfma_f32_16x16x32_bf16 v[20:23], v[164:167], v[188:191], v[20:23]
	v_mfma_f32_16x16x32_bf16 v[16:19], v[172:175], v[188:191], v[16:19]
	v_mfma_f32_16x16x32_bf16 v[12:15], v[164:167], v[196:199], v[12:15]
	v_mfma_f32_16x16x32_bf16 v[8:11], v[172:175], v[196:199], v[8:11]
	v_mfma_f32_16x16x32_bf16 v[4:7], v[164:167], v[204:207], v[4:7]
	v_mfma_f32_16x16x32_bf16 v[0:3], v[172:175], v[204:207], v[0:3]
	v_mfma_f32_16x16x32_bf16 v[28:31], v[168:171], v[184:187], v[28:31]
	v_mfma_f32_16x16x32_bf16 v[24:27], v[176:179], v[184:187], v[24:27]
	v_mfma_f32_16x16x32_bf16 v[20:23], v[168:171], v[192:195], v[20:23]
	v_mfma_f32_16x16x32_bf16 v[16:19], v[176:179], v[192:195], v[16:19]
	v_mfma_f32_16x16x32_bf16 v[12:15], v[168:171], v[200:203], v[12:15]
	v_mfma_f32_16x16x32_bf16 v[8:11], v[176:179], v[200:203], v[8:11]
	v_mfma_f32_16x16x32_bf16 v[4:7], v[168:171], v[212:215], v[4:7]
	v_mfma_f32_16x16x32_bf16 v[0:3], v[176:179], v[212:215], v[0:3]
	s_setprio 0
	s_barrier
	s_add_i32 s58, 0, 0x18000
	s_add_i32 s59, 0, 0x1c000
	v_add_u32_e32 v156, s58, v161
	v_add_u32_e32 v176, s59, v161
	ds_read_b128 v[144:147], v156
	ds_read_b128 v[148:151], v156 offset:1024
	ds_read_b128 v[152:155], v156 offset:2048
	ds_read_b128 v[156:159], v156 offset:3072
	ds_read_b128 v[164:167], v176
	ds_read_b128 v[168:171], v176 offset:1024
	ds_read_b128 v[172:175], v176 offset:2048
	ds_read_b128 v[176:179], v176 offset:3072
	v_lshl_add_u64 v[220:221], s[74:75], 0, v[128:129]
	s_mov_b32 m0, s77
	s_nop 0
	global_load_lds_dwordx4 v[220:221], off
	s_mov_b32 m0, s78
	s_nop 0
	global_load_lds_dwordx4 v[222:223], off
	s_add_u32 s74, s74, 0x20000
	s_addc_u32 s75, s75, 0
	s_mov_b32 m0, s79
	v_lshl_add_u64 v[224:225], s[74:75], 0, v[128:129]
	ds_read_b128 v[180:183], v163 offset:32768
	ds_read_b128 v[184:187], v163 offset:33792
	ds_read_b128 v[188:191], v163 offset:34816
	ds_read_b128 v[192:195], v163 offset:35840
	ds_read_b128 v[196:199], v163 offset:36864
	ds_read_b128 v[200:203], v163 offset:37888
	ds_read_b128 v[204:207], v163 offset:38912
	ds_read_b128 v[212:215], v163 offset:39936
	global_load_lds_dwordx4 v[224:225], off
	v_lshl_add_u64 v[224:225], s[74:75], 0, v[132:133]
	s_mov_b32 m0, s80
	s_nop 0
	global_load_lds_dwordx4 v[224:225], off
	s_waitcnt vmcnt(8)
	s_waitcnt lgkmcnt(0)
	s_barrier
	s_setprio 1
	s_waitcnt lgkmcnt(0)
	v_mfma_f32_16x16x32_bf16 v[124:127], v[144:147], v[180:183], v[124:127]
	v_mfma_f32_16x16x32_bf16 v[120:123], v[152:155], v[180:183], v[120:123]
	v_mfma_f32_16x16x32_bf16 v[116:119], v[144:147], v[188:191], v[116:119]
	v_mfma_f32_16x16x32_bf16 v[112:115], v[152:155], v[188:191], v[112:115]
	v_mfma_f32_16x16x32_bf16 v[108:111], v[144:147], v[196:199], v[108:111]
	v_mfma_f32_16x16x32_bf16 v[104:107], v[152:155], v[196:199], v[104:107]
	v_mfma_f32_16x16x32_bf16 v[100:103], v[144:147], v[204:207], v[100:103]
	v_mfma_f32_16x16x32_bf16 v[96:99], v[152:155], v[204:207], v[96:99]
	v_mfma_f32_16x16x32_bf16 v[124:127], v[148:151], v[184:187], v[124:127]
	v_mfma_f32_16x16x32_bf16 v[120:123], v[156:159], v[184:187], v[120:123]
	v_mfma_f32_16x16x32_bf16 v[116:119], v[148:151], v[192:195], v[116:119]
	v_mfma_f32_16x16x32_bf16 v[112:115], v[156:159], v[192:195], v[112:115]
	v_mfma_f32_16x16x32_bf16 v[108:111], v[148:151], v[200:203], v[108:111]
	v_mfma_f32_16x16x32_bf16 v[104:107], v[156:159], v[200:203], v[104:107]
	v_mfma_f32_16x16x32_bf16 v[100:103], v[148:151], v[212:215], v[100:103]
	v_mfma_f32_16x16x32_bf16 v[96:99], v[156:159], v[212:215], v[96:99]
	s_setprio 0
	s_setprio 1
	v_mfma_f32_16x16x32_bf16 v[92:95], v[164:167], v[180:183], v[92:95]
	v_mfma_f32_16x16x32_bf16 v[88:91], v[172:175], v[180:183], v[88:91]
	v_mfma_f32_16x16x32_bf16 v[84:87], v[164:167], v[188:191], v[84:87]
	v_mfma_f32_16x16x32_bf16 v[80:83], v[172:175], v[188:191], v[80:83]
	v_mfma_f32_16x16x32_bf16 v[76:79], v[164:167], v[196:199], v[76:79]
	v_mfma_f32_16x16x32_bf16 v[72:75], v[172:175], v[196:199], v[72:75]
	v_mfma_f32_16x16x32_bf16 v[68:71], v[164:167], v[204:207], v[68:71]
	v_mfma_f32_16x16x32_bf16 v[64:67], v[172:175], v[204:207], v[64:67]
	v_mfma_f32_16x16x32_bf16 v[92:95], v[168:171], v[184:187], v[92:95]
	v_mfma_f32_16x16x32_bf16 v[88:91], v[176:179], v[184:187], v[88:91]
	v_mfma_f32_16x16x32_bf16 v[84:87], v[168:171], v[192:195], v[84:87]
	v_mfma_f32_16x16x32_bf16 v[80:83], v[176:179], v[192:195], v[80:83]
	v_mfma_f32_16x16x32_bf16 v[76:79], v[168:171], v[200:203], v[76:79]
	v_mfma_f32_16x16x32_bf16 v[72:75], v[176:179], v[200:203], v[72:75]
	v_mfma_f32_16x16x32_bf16 v[68:71], v[168:171], v[212:215], v[68:71]
	v_mfma_f32_16x16x32_bf16 v[64:67], v[176:179], v[212:215], v[64:67]
	s_setprio 0
	s_barrier
	s_add_i32 s58, s58, s76
	v_lshl_add_u64 v[216:217], v[216:217], 0, s[38:39]
	s_mov_b32 m0, s58
	ds_read_b128 v[180:183], v163 offset:49152
	ds_read_b128 v[184:187], v163 offset:50176
	ds_read_b128 v[188:191], v163 offset:51200
	ds_read_b128 v[192:195], v163 offset:52224
	ds_read_b128 v[196:199], v163 offset:53248
	ds_read_b128 v[200:203], v163 offset:54272
	ds_read_b128 v[204:207], v163 offset:55296
	ds_read_b128 v[212:215], v163 offset:56320
	global_load_lds_dwordx4 v[216:217], off
	s_add_i32 m0, s58, 0x2000
	s_add_u32 s72, s72, 0x20080
	v_lshl_add_u64 v[216:217], v[218:219], 0, s[38:39]
	s_addc_u32 s73, s73, 0
	s_add_i32 s58, s59, s76
	global_load_lds_dwordx4 v[216:217], off
	v_lshl_add_u64 v[216:217], s[72:73], 0, v[130:131]
	s_mov_b32 m0, s58
	s_nop 0
	global_load_lds_dwordx4 v[216:217], off
	v_lshl_add_u64 v[216:217], s[72:73], 0, v[134:135]
	s_add_i32 m0, s58, 0x2000
	s_nop 0
	global_load_lds_dwordx4 v[216:217], off
	v_lshl_add_u64 v[216:217], v[220:221], 0, s[38:39]
	s_mov_b32 m0, s81
	s_nop 0
	global_load_lds_dwordx4 v[216:217], off
	v_lshl_add_u64 v[216:217], v[222:223], 0, s[38:39]
	s_mov_b32 m0, s82
	s_nop 0
	global_load_lds_dwordx4 v[216:217], off
	s_waitcnt vmcnt(6)
	s_waitcnt lgkmcnt(0)
	s_barrier
	s_setprio 1
	s_waitcnt lgkmcnt(0)
	v_mfma_f32_16x16x32_bf16 v[60:63], v[144:147], v[180:183], v[60:63]
	v_mfma_f32_16x16x32_bf16 v[56:59], v[152:155], v[180:183], v[56:59]
	v_mfma_f32_16x16x32_bf16 v[52:55], v[144:147], v[188:191], v[52:55]
	v_mfma_f32_16x16x32_bf16 v[48:51], v[152:155], v[188:191], v[48:51]
	v_mfma_f32_16x16x32_bf16 v[44:47], v[144:147], v[196:199], v[44:47]
	v_mfma_f32_16x16x32_bf16 v[40:43], v[152:155], v[196:199], v[40:43]
	v_mfma_f32_16x16x32_bf16 v[36:39], v[144:147], v[204:207], v[36:39]
	v_mfma_f32_16x16x32_bf16 v[32:35], v[152:155], v[204:207], v[32:35]
	v_mfma_f32_16x16x32_bf16 v[60:63], v[148:151], v[184:187], v[60:63]
	v_mfma_f32_16x16x32_bf16 v[56:59], v[156:159], v[184:187], v[56:59]
	v_mfma_f32_16x16x32_bf16 v[52:55], v[148:151], v[192:195], v[52:55]
	v_mfma_f32_16x16x32_bf16 v[48:51], v[156:159], v[192:195], v[48:51]
	v_mfma_f32_16x16x32_bf16 v[44:47], v[148:151], v[200:203], v[44:47]
	v_mfma_f32_16x16x32_bf16 v[40:43], v[156:159], v[200:203], v[40:43]
	v_mfma_f32_16x16x32_bf16 v[36:39], v[148:151], v[212:215], v[36:39]
	v_mfma_f32_16x16x32_bf16 v[32:35], v[156:159], v[212:215], v[32:35]
	s_setprio 0
	s_setprio 1
	v_mfma_f32_16x16x32_bf16 v[28:31], v[164:167], v[180:183], v[28:31]
	v_mfma_f32_16x16x32_bf16 v[24:27], v[172:175], v[180:183], v[24:27]
	v_mfma_f32_16x16x32_bf16 v[20:23], v[164:167], v[188:191], v[20:23]
	v_mfma_f32_16x16x32_bf16 v[16:19], v[172:175], v[188:191], v[16:19]
	v_mfma_f32_16x16x32_bf16 v[12:15], v[164:167], v[196:199], v[12:15]
	v_mfma_f32_16x16x32_bf16 v[8:11], v[172:175], v[196:199], v[8:11]
	v_mfma_f32_16x16x32_bf16 v[4:7], v[164:167], v[204:207], v[4:7]
	v_mfma_f32_16x16x32_bf16 v[0:3], v[172:175], v[204:207], v[0:3]
	v_mfma_f32_16x16x32_bf16 v[28:31], v[168:171], v[184:187], v[28:31]
	v_mfma_f32_16x16x32_bf16 v[24:27], v[176:179], v[184:187], v[24:27]
	v_mfma_f32_16x16x32_bf16 v[20:23], v[168:171], v[192:195], v[20:23]
	v_mfma_f32_16x16x32_bf16 v[16:19], v[176:179], v[192:195], v[16:19]
	v_mfma_f32_16x16x32_bf16 v[12:15], v[168:171], v[200:203], v[12:15]
	v_mfma_f32_16x16x32_bf16 v[8:11], v[176:179], v[200:203], v[8:11]
	v_mfma_f32_16x16x32_bf16 v[4:7], v[168:171], v[212:215], v[4:7]
	v_mfma_f32_16x16x32_bf16 v[0:3], v[176:179], v[212:215], v[0:3]
	s_setprio 0
	s_barrier
	s_add_i32 s95, s95, 2
	s_add_u32 s70, s70, 0x100
	s_addc_u32 s71, s71, 0
	s_add_u32 s93, s93, 0x100
	s_addc_u32 s94, s94, 0
	s_cmp_gt_u32 s95, 5
	s_cbranch_scc0 .LBB0_462
	s_and_b64 vcc, exec, s[40:41]
	s_cbranch_vccz .LBB0_465
	s_barrier

.LBB0_544:
	ds_read_b128 v[100:103], v199
	ds_read_b128 v[108:111], v199 offset:1024
	ds_read_b128 v[112:115], v199 offset:2048
	ds_read_b128 v[116:119], v199 offset:3072
	ds_read_b128 v[156:159], v200
	ds_read_b128 v[160:163], v200 offset:1024
	ds_read_b128 v[164:167], v200 offset:2048
	ds_read_b128 v[168:171], v200 offset:3072
	s_add_u32 s56, s54, 0xfffc0080
	s_addc_u32 s57, s55, -1
	s_cmp_eq_u32 s88, 12
	s_cselect_b32 s65, s43, s57
	s_cselect_b32 s64, s49, s56
	s_cselect_b32 s57, s41, s33
	s_cselect_b32 s56, s53, s87
	v_lshl_add_u64 v[216:217], s[54:55], 0, v[148:149]
	s_add_i32 m0, s67, 0xc000
	ds_read_b128 v[172:175], v201
	ds_read_b128 v[176:179], v201 offset:1024
	ds_read_b128 v[180:183], v201 offset:2048
	ds_read_b128 v[184:187], v201 offset:3072
	ds_read_b128 v[188:191], v201 offset:4096
	ds_read_b128 v[192:195], v201 offset:5120
	ds_read_b128 v[204:207], v201 offset:6144
	ds_read_b128 v[212:215], v201 offset:7168
	global_load_lds_dwordx4 v[216:217], off
	v_lshl_add_u64 v[216:217], s[54:55], 0, v[150:151]
	s_add_i32 m0, s67, 0xe000
	s_nop 0
	global_load_lds_dwordx4 v[216:217], off
	s_waitcnt vmcnt(8)
	s_waitcnt lgkmcnt(0)
	s_barrier
	s_setprio 1
	s_waitcnt lgkmcnt(0)
	v_mfma_f32_16x16x32_bf16 v[140:143], v[100:103], v[172:175], v[140:143]
	v_mfma_f32_16x16x32_bf16 v[136:139], v[112:115], v[172:175], v[136:139]
	v_mfma_f32_16x16x32_bf16 v[124:127], v[100:103], v[180:183], v[124:127]
	v_mfma_f32_16x16x32_bf16 v[120:123], v[112:115], v[180:183], v[120:123]
	v_mfma_f32_16x16x32_bf16 v[92:95], v[100:103], v[188:191], v[92:95]
	v_mfma_f32_16x16x32_bf16 v[88:91], v[112:115], v[188:191], v[88:91]
	v_mfma_f32_16x16x32_bf16 v[76:79], v[100:103], v[204:207], v[76:79]
	v_mfma_f32_16x16x32_bf16 v[72:75], v[112:115], v[204:207], v[72:75]
	v_mfma_f32_16x16x32_bf16 v[140:143], v[108:111], v[176:179], v[140:143]
	v_mfma_f32_16x16x32_bf16 v[136:139], v[116:119], v[176:179], v[136:139]
	v_mfma_f32_16x16x32_bf16 v[124:127], v[108:111], v[184:187], v[124:127]
	v_mfma_f32_16x16x32_bf16 v[120:123], v[116:119], v[184:187], v[120:123]
	v_mfma_f32_16x16x32_bf16 v[92:95], v[108:111], v[192:195], v[92:95]
	v_mfma_f32_16x16x32_bf16 v[88:91], v[116:119], v[192:195], v[88:91]
	v_mfma_f32_16x16x32_bf16 v[76:79], v[108:111], v[212:215], v[76:79]
	v_mfma_f32_16x16x32_bf16 v[72:75], v[116:119], v[212:215], v[72:75]
	s_setprio 0
	s_setprio 1
	v_mfma_f32_16x16x32_bf16 v[132:135], v[156:159], v[172:175], v[132:135]
	v_mfma_f32_16x16x32_bf16 v[128:131], v[164:167], v[172:175], v[128:131]
	v_mfma_f32_16x16x32_bf16 v[104:107], v[156:159], v[180:183], v[104:107]
	v_mfma_f32_16x16x32_bf16 v[96:99], v[164:167], v[180:183], v[96:99]
	v_mfma_f32_16x16x32_bf16 v[84:87], v[156:159], v[188:191], v[84:87]
	v_mfma_f32_16x16x32_bf16 v[80:83], v[164:167], v[188:191], v[80:83]
	v_mfma_f32_16x16x32_bf16 v[68:71], v[156:159], v[204:207], v[68:71]
	v_mfma_f32_16x16x32_bf16 v[64:67], v[164:167], v[204:207], v[64:67]
	v_mfma_f32_16x16x32_bf16 v[132:135], v[160:163], v[176:179], v[132:135]
	v_mfma_f32_16x16x32_bf16 v[128:131], v[168:171], v[176:179], v[128:131]
	v_mfma_f32_16x16x32_bf16 v[104:107], v[160:163], v[184:187], v[104:107]
	v_mfma_f32_16x16x32_bf16 v[96:99], v[168:171], v[184:187], v[96:99]
	v_mfma_f32_16x16x32_bf16 v[84:87], v[160:163], v[192:195], v[84:87]
	v_mfma_f32_16x16x32_bf16 v[80:83], v[168:171], v[192:195], v[80:83]
	v_mfma_f32_16x16x32_bf16 v[68:71], v[160:163], v[212:215], v[68:71]
	v_mfma_f32_16x16x32_bf16 v[64:67], v[168:171], v[212:215], v[64:67]
	s_setprio 0
	s_barrier
	s_add_i32 s58, s85, s66
	v_lshl_add_u64 v[216:217], s[56:57], 0, v[144:145]
	s_mov_b32 m0, s58
	ds_read_b128 v[172:175], v201 offset:16384
	ds_read_b128 v[176:179], v201 offset:17408
	ds_read_b128 v[180:183], v201 offset:18432
	ds_read_b128 v[184:187], v201 offset:19456
	ds_read_b128 v[188:191], v201 offset:20480
	ds_read_b128 v[192:195], v201 offset:21504
	ds_read_b128 v[204:207], v201 offset:22528
	ds_read_b128 v[212:215], v201 offset:23552
	global_load_lds_dwordx4 v[216:217], off
	s_add_i32 m0, s58, 0x2000
	s_add_u32 s90, s56, 0x40000
	v_lshl_add_u64 v[218:219], s[56:57], 0, v[146:147]
	s_addc_u32 s91, s57, 0
	s_add_i32 s58, s86, s66
	global_load_lds_dwordx4 v[218:219], off
	v_lshl_add_u64 v[220:221], s[90:91], 0, v[144:145]
	s_mov_b32 m0, s58
	v_lshl_add_u64 v[222:223], s[64:65], 0, v[146:147]
	global_load_lds_dwordx4 v[220:221], off
	v_lshl_add_u64 v[220:221], s[90:91], 0, v[146:147]
	s_add_i32 m0, s58, 0x2000
	s_nop 0
	global_load_lds_dwordx4 v[220:221], off
	s_waitcnt vmcnt(6)
	s_waitcnt lgkmcnt(0)
	s_barrier
	s_setprio 1
	s_waitcnt lgkmcnt(0)
	v_mfma_f32_16x16x32_bf16 v[60:63], v[100:103], v[172:175], v[60:63]
	v_mfma_f32_16x16x32_bf16 v[56:59], v[112:115], v[172:175], v[56:59]
	v_mfma_f32_16x16x32_bf16 v[44:47], v[100:103], v[180:183], v[44:47]
	v_mfma_f32_16x16x32_bf16 v[40:43], v[112:115], v[180:183], v[40:43]
	v_mfma_f32_16x16x32_bf16 v[28:31], v[100:103], v[188:191], v[28:31]
	v_mfma_f32_16x16x32_bf16 v[24:27], v[112:115], v[188:191], v[24:27]
	v_mfma_f32_16x16x32_bf16 v[12:15], v[100:103], v[204:207], v[12:15]
	v_mfma_f32_16x16x32_bf16 v[8:11], v[112:115], v[204:207], v[8:11]
	v_mfma_f32_16x16x32_bf16 v[60:63], v[108:111], v[176:179], v[60:63]
	v_mfma_f32_16x16x32_bf16 v[56:59], v[116:119], v[176:179], v[56:59]
	v_mfma_f32_16x16x32_bf16 v[44:47], v[108:111], v[184:187], v[44:47]
	v_mfma_f32_16x16x32_bf16 v[40:43], v[116:119], v[184:187], v[40:43]
	v_mfma_f32_16x16x32_bf16 v[28:31], v[108:111], v[192:195], v[28:31]
	v_mfma_f32_16x16x32_bf16 v[24:27], v[116:119], v[192:195], v[24:27]
	v_mfma_f32_16x16x32_bf16 v[12:15], v[108:111], v[212:215], v[12:15]
	v_mfma_f32_16x16x32_bf16 v[8:11], v[116:119], v[212:215], v[8:11]
	s_setprio 0
	s_setprio 1
	v_mfma_f32_16x16x32_bf16 v[52:55], v[156:159], v[172:175], v[52:55]
	v_mfma_f32_16x16x32_bf16 v[48:51], v[164:167], v[172:175], v[48:51]
	v_mfma_f32_16x16x32_bf16 v[36:39], v[156:159], v[180:183], v[36:39]
	v_mfma_f32_16x16x32_bf16 v[32:35], v[164:167], v[180:183], v[32:35]
	v_mfma_f32_16x16x32_bf16 v[20:23], v[156:159], v[188:191], v[20:23]
	v_mfma_f32_16x16x32_bf16 v[16:19], v[164:167], v[188:191], v[16:19]
	v_mfma_f32_16x16x32_bf16 v[4:7], v[156:159], v[204:207], v[4:7]
	v_mfma_f32_16x16x32_bf16 v[0:3], v[164:167], v[204:207], v[0:3]
	v_mfma_f32_16x16x32_bf16 v[52:55], v[160:163], v[176:179], v[52:55]
	v_mfma_f32_16x16x32_bf16 v[48:51], v[168:171], v[176:179], v[48:51]
	v_mfma_f32_16x16x32_bf16 v[36:39], v[160:163], v[184:187], v[36:39]
	v_mfma_f32_16x16x32_bf16 v[32:35], v[168:171], v[184:187], v[32:35]
	v_mfma_f32_16x16x32_bf16 v[20:23], v[160:163], v[192:195], v[20:23]
	v_mfma_f32_16x16x32_bf16 v[16:19], v[168:171], v[192:195], v[16:19]
	v_mfma_f32_16x16x32_bf16 v[4:7], v[160:163], v[212:215], v[4:7]
	v_mfma_f32_16x16x32_bf16 v[0:3], v[168:171], v[212:215], v[0:3]
	s_setprio 0
	s_barrier
	s_add_i32 s58, 0, 0x18000
	s_add_i32 s59, 0, 0x1c000
	v_add_u32_e32 v116, s58, v197
	v_add_u32_e32 v168, s59, v197
	ds_read_b128 v[100:103], v116
	ds_read_b128 v[108:111], v116 offset:1024
	ds_read_b128 v[112:115], v116 offset:2048
	ds_read_b128 v[116:119], v116 offset:3072
	ds_read_b128 v[156:159], v168
	ds_read_b128 v[160:163], v168 offset:1024
	ds_read_b128 v[164:167], v168 offset:2048
	ds_read_b128 v[168:171], v168 offset:3072
	v_lshl_add_u64 v[220:221], s[64:65], 0, v[144:145]
	s_mov_b32 m0, s67
	s_nop 0
	global_load_lds_dwordx4 v[220:221], off
	s_mov_b32 m0, s68
	s_nop 0
	global_load_lds_dwordx4 v[222:223], off
	s_add_u32 s64, s64, 0x40000
	s_addc_u32 s65, s65, 0
	s_mov_b32 m0, s69
	v_lshl_add_u64 v[224:225], s[64:65], 0, v[144:145]
	ds_read_b128 v[172:175], v201 offset:32768
	ds_read_b128 v[176:179], v201 offset:33792
	ds_read_b128 v[180:183], v201 offset:34816
	ds_read_b128 v[184:187], v201 offset:35840
	ds_read_b128 v[188:191], v201 offset:36864
	ds_read_b128 v[192:195], v201 offset:37888
	ds_read_b128 v[204:207], v201 offset:38912
	ds_read_b128 v[212:215], v201 offset:39936
	global_load_lds_dwordx4 v[224:225], off
	v_lshl_add_u64 v[224:225], s[64:65], 0, v[146:147]
	s_mov_b32 m0, s70
	s_nop 0
	global_load_lds_dwordx4 v[224:225], off
	s_waitcnt vmcnt(8)
	s_waitcnt lgkmcnt(0)
	s_barrier
	s_setprio 1
	s_waitcnt lgkmcnt(0)
	v_mfma_f32_16x16x32_bf16 v[140:143], v[100:103], v[172:175], v[140:143]
	v_mfma_f32_16x16x32_bf16 v[136:139], v[112:115], v[172:175], v[136:139]
	v_mfma_f32_16x16x32_bf16 v[124:127], v[100:103], v[180:183], v[124:127]
	v_mfma_f32_16x16x32_bf16 v[120:123], v[112:115], v[180:183], v[120:123]
	v_mfma_f32_16x16x32_bf16 v[92:95], v[100:103], v[188:191], v[92:95]
	v_mfma_f32_16x16x32_bf16 v[88:91], v[112:115], v[188:191], v[88:91]
	v_mfma_f32_16x16x32_bf16 v[76:79], v[100:103], v[204:207], v[76:79]
	v_mfma_f32_16x16x32_bf16 v[72:75], v[112:115], v[204:207], v[72:75]
	v_mfma_f32_16x16x32_bf16 v[140:143], v[108:111], v[176:179], v[140:143]
	v_mfma_f32_16x16x32_bf16 v[136:139], v[116:119], v[176:179], v[136:139]
	v_mfma_f32_16x16x32_bf16 v[124:127], v[108:111], v[184:187], v[124:127]
	v_mfma_f32_16x16x32_bf16 v[120:123], v[116:119], v[184:187], v[120:123]
	v_mfma_f32_16x16x32_bf16 v[92:95], v[108:111], v[192:195], v[92:95]
	v_mfma_f32_16x16x32_bf16 v[88:91], v[116:119], v[192:195], v[88:91]
	v_mfma_f32_16x16x32_bf16 v[76:79], v[108:111], v[212:215], v[76:79]
	v_mfma_f32_16x16x32_bf16 v[72:75], v[116:119], v[212:215], v[72:75]
	s_setprio 0
	s_setprio 1
	v_mfma_f32_16x16x32_bf16 v[132:135], v[156:159], v[172:175], v[132:135]
	v_mfma_f32_16x16x32_bf16 v[128:131], v[164:167], v[172:175], v[128:131]
	v_mfma_f32_16x16x32_bf16 v[104:107], v[156:159], v[180:183], v[104:107]
	v_mfma_f32_16x16x32_bf16 v[96:99], v[164:167], v[180:183], v[96:99]
	v_mfma_f32_16x16x32_bf16 v[84:87], v[156:159], v[188:191], v[84:87]
	v_mfma_f32_16x16x32_bf16 v[80:83], v[164:167], v[188:191], v[80:83]
	v_mfma_f32_16x16x32_bf16 v[68:71], v[156:159], v[204:207], v[68:71]
	v_mfma_f32_16x16x32_bf16 v[64:67], v[164:167], v[204:207], v[64:67]
	v_mfma_f32_16x16x32_bf16 v[132:135], v[160:163], v[176:179], v[132:135]
	v_mfma_f32_16x16x32_bf16 v[128:131], v[168:171], v[176:179], v[128:131]
	v_mfma_f32_16x16x32_bf16 v[104:107], v[160:163], v[184:187], v[104:107]
	v_mfma_f32_16x16x32_bf16 v[96:99], v[168:171], v[184:187], v[96:99]
	v_mfma_f32_16x16x32_bf16 v[84:87], v[160:163], v[192:195], v[84:87]
	v_mfma_f32_16x16x32_bf16 v[80:83], v[168:171], v[192:195], v[80:83]
	v_mfma_f32_16x16x32_bf16 v[68:71], v[160:163], v[212:215], v[68:71]
	v_mfma_f32_16x16x32_bf16 v[64:67], v[168:171], v[212:215], v[64:67]
	s_setprio 0
	s_barrier
	s_add_i32 s58, s58, s66
	v_lshl_add_u64 v[216:217], v[216:217], 0, s[36:37]
	s_mov_b32 m0, s58
	ds_read_b128 v[172:175], v201 offset:49152
	ds_read_b128 v[176:179], v201 offset:50176
	ds_read_b128 v[180:183], v201 offset:51200
	ds_read_b128 v[184:187], v201 offset:52224
	ds_read_b128 v[188:191], v201 offset:53248
	ds_read_b128 v[192:195], v201 offset:54272
	ds_read_b128 v[204:207], v201 offset:55296
	ds_read_b128 v[212:215], v201 offset:56320
	global_load_lds_dwordx4 v[216:217], off
	s_add_i32 m0, s58, 0x2000
	s_add_u32 s56, s56, 0x40080
	v_lshl_add_u64 v[216:217], v[218:219], 0, s[36:37]
	s_addc_u32 s57, s57, 0
	s_add_i32 s58, s59, s66
	global_load_lds_dwordx4 v[216:217], off
	v_lshl_add_u64 v[216:217], s[56:57], 0, v[144:145]
	s_mov_b32 m0, s58
	s_nop 0
	global_load_lds_dwordx4 v[216:217], off
	v_lshl_add_u64 v[216:217], s[56:57], 0, v[146:147]
	s_add_i32 m0, s58, 0x2000
	s_nop 0
	global_load_lds_dwordx4 v[216:217], off
	v_lshl_add_u64 v[216:217], v[220:221], 0, s[36:37]
	s_mov_b32 m0, s80
	s_nop 0
	global_load_lds_dwordx4 v[216:217], off
	v_lshl_add_u64 v[216:217], v[222:223], 0, s[36:37]
	s_mov_b32 m0, s81
	s_nop 0
	global_load_lds_dwordx4 v[216:217], off
	s_waitcnt vmcnt(6)
	s_waitcnt lgkmcnt(0)
	s_barrier
	s_setprio 1
	s_waitcnt lgkmcnt(0)
	v_mfma_f32_16x16x32_bf16 v[60:63], v[100:103], v[172:175], v[60:63]
	v_mfma_f32_16x16x32_bf16 v[56:59], v[112:115], v[172:175], v[56:59]
	v_mfma_f32_16x16x32_bf16 v[44:47], v[100:103], v[180:183], v[44:47]
	v_mfma_f32_16x16x32_bf16 v[40:43], v[112:115], v[180:183], v[40:43]
	v_mfma_f32_16x16x32_bf16 v[28:31], v[100:103], v[188:191], v[28:31]
	v_mfma_f32_16x16x32_bf16 v[24:27], v[112:115], v[188:191], v[24:27]
	v_mfma_f32_16x16x32_bf16 v[12:15], v[100:103], v[204:207], v[12:15]
	v_mfma_f32_16x16x32_bf16 v[8:11], v[112:115], v[204:207], v[8:11]
	v_mfma_f32_16x16x32_bf16 v[60:63], v[108:111], v[176:179], v[60:63]
	v_mfma_f32_16x16x32_bf16 v[56:59], v[116:119], v[176:179], v[56:59]
	v_mfma_f32_16x16x32_bf16 v[44:47], v[108:111], v[184:187], v[44:47]
	v_mfma_f32_16x16x32_bf16 v[40:43], v[116:119], v[184:187], v[40:43]
	v_mfma_f32_16x16x32_bf16 v[28:31], v[108:111], v[192:195], v[28:31]
	v_mfma_f32_16x16x32_bf16 v[24:27], v[116:119], v[192:195], v[24:27]
	v_mfma_f32_16x16x32_bf16 v[12:15], v[108:111], v[212:215], v[12:15]
	v_mfma_f32_16x16x32_bf16 v[8:11], v[116:119], v[212:215], v[8:11]
	s_setprio 0
	s_setprio 1
	v_mfma_f32_16x16x32_bf16 v[52:55], v[156:159], v[172:175], v[52:55]
	v_mfma_f32_16x16x32_bf16 v[48:51], v[164:167], v[172:175], v[48:51]
	v_mfma_f32_16x16x32_bf16 v[36:39], v[156:159], v[180:183], v[36:39]
	v_mfma_f32_16x16x32_bf16 v[32:35], v[164:167], v[180:183], v[32:35]
	v_mfma_f32_16x16x32_bf16 v[20:23], v[156:159], v[188:191], v[20:23]
	v_mfma_f32_16x16x32_bf16 v[16:19], v[164:167], v[188:191], v[16:19]
	v_mfma_f32_16x16x32_bf16 v[4:7], v[156:159], v[204:207], v[4:7]
	v_mfma_f32_16x16x32_bf16 v[0:3], v[164:167], v[204:207], v[0:3]
	v_mfma_f32_16x16x32_bf16 v[52:55], v[160:163], v[176:179], v[52:55]
	v_mfma_f32_16x16x32_bf16 v[48:51], v[168:171], v[176:179], v[48:51]
	v_mfma_f32_16x16x32_bf16 v[36:39], v[160:163], v[184:187], v[36:39]
	v_mfma_f32_16x16x32_bf16 v[32:35], v[168:171], v[184:187], v[32:35]
	v_mfma_f32_16x16x32_bf16 v[20:23], v[160:163], v[192:195], v[20:23]
	v_mfma_f32_16x16x32_bf16 v[16:19], v[168:171], v[192:195], v[16:19]
	v_mfma_f32_16x16x32_bf16 v[4:7], v[160:163], v[212:215], v[4:7]
	v_mfma_f32_16x16x32_bf16 v[0:3], v[168:171], v[212:215], v[0:3]
	s_setprio 0
	s_barrier
	s_add_i32 s88, s88, 2
	s_add_u32 s54, s54, 0x100
	s_addc_u32 s55, s55, 0
	s_add_u32 s87, s87, 0x100
	s_addc_u32 s33, s33, 0
	s_cmp_gt_u32 s88, 13
	s_cbranch_scc0 .LBB0_544
	s_and_b64 vcc, exec, s[38:39]
	s_cbranch_vccz .LBB0_547
	s_barrier

.LBB0_639:
	ds_read_b128 v[144:147], v151
	ds_read_b128 v[154:157], v151 offset:1024
	ds_read_b128 v[158:161], v151 offset:2048
	ds_read_b128 v[162:165], v151 offset:3072
	ds_read_b128 v[166:169], v152
	ds_read_b128 v[170:173], v152 offset:1024
	ds_read_b128 v[174:177], v152 offset:2048
	ds_read_b128 v[178:181], v152 offset:3072
	s_add_u32 s40, s38, 0xfffc0080
	s_addc_u32 s41, s39, -1
	s_cmp_eq_u32 s68, 12
	s_cselect_b32 s43, s21, s41
	s_cselect_b32 s42, s65, s40
	s_cselect_b32 s41, s17, s33
	s_cselect_b32 s40, s66, s67
	v_lshl_add_u64 v[206:207], s[38:39], 0, v[136:137]
	s_add_i32 m0, s37, 0xc000
	ds_read_b128 v[182:185], v153
	ds_read_b128 v[186:189], v153 offset:1024
	ds_read_b128 v[190:193], v153 offset:2048
	ds_read_b128 v[194:197], v153 offset:3072
	ds_read_b128 v[198:201], v153 offset:4096
	ds_read_b128 v[202:205], v153 offset:5120
	ds_read_b128 v[212:215], v153 offset:6144
	ds_read_b128 v[216:219], v153 offset:7168
	global_load_lds_dwordx4 v[206:207], off
	v_lshl_add_u64 v[206:207], s[38:39], 0, v[138:139]
	s_add_i32 m0, s37, 0xe000
	s_nop 0
	global_load_lds_dwordx4 v[206:207], off
	s_waitcnt vmcnt(8)
	s_waitcnt lgkmcnt(0)
	s_barrier
	s_setprio 1
	s_waitcnt lgkmcnt(0)
	v_mfma_f32_16x16x32_bf16 v[124:127], v[144:147], v[182:185], v[124:127]
	v_mfma_f32_16x16x32_bf16 v[116:119], v[158:161], v[182:185], v[116:119]
	v_mfma_f32_16x16x32_bf16 v[108:111], v[144:147], v[190:193], v[108:111]
	v_mfma_f32_16x16x32_bf16 v[100:103], v[158:161], v[190:193], v[100:103]
	v_mfma_f32_16x16x32_bf16 v[92:95], v[144:147], v[198:201], v[92:95]
	v_mfma_f32_16x16x32_bf16 v[84:87], v[158:161], v[198:201], v[84:87]
	v_mfma_f32_16x16x32_bf16 v[76:79], v[144:147], v[212:215], v[76:79]
	v_mfma_f32_16x16x32_bf16 v[68:71], v[158:161], v[212:215], v[68:71]
	v_mfma_f32_16x16x32_bf16 v[124:127], v[154:157], v[186:189], v[124:127]
	v_mfma_f32_16x16x32_bf16 v[116:119], v[162:165], v[186:189], v[116:119]
	v_mfma_f32_16x16x32_bf16 v[108:111], v[154:157], v[194:197], v[108:111]
	v_mfma_f32_16x16x32_bf16 v[100:103], v[162:165], v[194:197], v[100:103]
	v_mfma_f32_16x16x32_bf16 v[92:95], v[154:157], v[202:205], v[92:95]
	v_mfma_f32_16x16x32_bf16 v[84:87], v[162:165], v[202:205], v[84:87]
	v_mfma_f32_16x16x32_bf16 v[76:79], v[154:157], v[216:219], v[76:79]
	v_mfma_f32_16x16x32_bf16 v[68:71], v[162:165], v[216:219], v[68:71]
	s_setprio 0
	s_setprio 1
	v_mfma_f32_16x16x32_bf16 v[120:123], v[166:169], v[182:185], v[120:123]
	v_mfma_f32_16x16x32_bf16 v[112:115], v[174:177], v[182:185], v[112:115]
	v_mfma_f32_16x16x32_bf16 v[104:107], v[166:169], v[190:193], v[104:107]
	v_mfma_f32_16x16x32_bf16 v[96:99], v[174:177], v[190:193], v[96:99]
	v_mfma_f32_16x16x32_bf16 v[88:91], v[166:169], v[198:201], v[88:91]
	v_mfma_f32_16x16x32_bf16 v[80:83], v[174:177], v[198:201], v[80:83]
	v_mfma_f32_16x16x32_bf16 v[72:75], v[166:169], v[212:215], v[72:75]
	v_mfma_f32_16x16x32_bf16 v[64:67], v[174:177], v[212:215], v[64:67]
	v_mfma_f32_16x16x32_bf16 v[120:123], v[170:173], v[186:189], v[120:123]
	v_mfma_f32_16x16x32_bf16 v[112:115], v[178:181], v[186:189], v[112:115]
	v_mfma_f32_16x16x32_bf16 v[104:107], v[170:173], v[194:197], v[104:107]
	v_mfma_f32_16x16x32_bf16 v[96:99], v[178:181], v[194:197], v[96:99]
	v_mfma_f32_16x16x32_bf16 v[88:91], v[170:173], v[202:205], v[88:91]
	v_mfma_f32_16x16x32_bf16 v[80:83], v[178:181], v[202:205], v[80:83]
	v_mfma_f32_16x16x32_bf16 v[72:75], v[170:173], v[216:219], v[72:75]
	v_mfma_f32_16x16x32_bf16 v[64:67], v[178:181], v[216:219], v[64:67]
	s_setprio 0
	s_barrier
	s_add_i32 s58, s55, s44
	v_lshl_add_u64 v[206:207], s[40:41], 0, v[132:133]
	s_mov_b32 m0, s58
	ds_read_b128 v[182:185], v153 offset:16384
	ds_read_b128 v[186:189], v153 offset:17408
	ds_read_b128 v[190:193], v153 offset:18432
	ds_read_b128 v[194:197], v153 offset:19456
	ds_read_b128 v[198:201], v153 offset:20480
	ds_read_b128 v[202:205], v153 offset:21504
	ds_read_b128 v[212:215], v153 offset:22528
	ds_read_b128 v[216:219], v153 offset:23552
	global_load_lds_dwordx4 v[206:207], off
	s_add_i32 m0, s58, 0x2000
	s_add_u32 s70, s40, 0x40000
	v_lshl_add_u64 v[220:221], s[40:41], 0, v[128:129]
	s_addc_u32 s71, s41, 0
	s_add_i32 s58, s56, s44
	global_load_lds_dwordx4 v[220:221], off
	v_lshl_add_u64 v[222:223], s[70:71], 0, v[132:133]
	s_mov_b32 m0, s58
	v_lshl_add_u64 v[224:225], s[42:43], 0, v[130:131]
	global_load_lds_dwordx4 v[222:223], off
	v_lshl_add_u64 v[222:223], s[70:71], 0, v[128:129]
	s_add_i32 m0, s58, 0x2000
	s_nop 0
	global_load_lds_dwordx4 v[222:223], off
	s_waitcnt vmcnt(6)
	s_waitcnt lgkmcnt(0)
	s_barrier
	s_setprio 1
	s_waitcnt lgkmcnt(0)
	v_mfma_f32_16x16x32_bf16 v[60:63], v[144:147], v[182:185], v[60:63]
	v_mfma_f32_16x16x32_bf16 v[52:55], v[158:161], v[182:185], v[52:55]
	v_mfma_f32_16x16x32_bf16 v[44:47], v[144:147], v[190:193], v[44:47]
	v_mfma_f32_16x16x32_bf16 v[36:39], v[158:161], v[190:193], v[36:39]
	v_mfma_f32_16x16x32_bf16 v[28:31], v[144:147], v[198:201], v[28:31]
	v_mfma_f32_16x16x32_bf16 v[20:23], v[158:161], v[198:201], v[20:23]
	v_mfma_f32_16x16x32_bf16 v[12:15], v[144:147], v[212:215], v[12:15]
	v_mfma_f32_16x16x32_bf16 v[4:7], v[158:161], v[212:215], v[4:7]
	v_mfma_f32_16x16x32_bf16 v[60:63], v[154:157], v[186:189], v[60:63]
	v_mfma_f32_16x16x32_bf16 v[52:55], v[162:165], v[186:189], v[52:55]
	v_mfma_f32_16x16x32_bf16 v[44:47], v[154:157], v[194:197], v[44:47]
	v_mfma_f32_16x16x32_bf16 v[36:39], v[162:165], v[194:197], v[36:39]
	v_mfma_f32_16x16x32_bf16 v[28:31], v[154:157], v[202:205], v[28:31]
	v_mfma_f32_16x16x32_bf16 v[20:23], v[162:165], v[202:205], v[20:23]
	v_mfma_f32_16x16x32_bf16 v[12:15], v[154:157], v[216:219], v[12:15]
	v_mfma_f32_16x16x32_bf16 v[4:7], v[162:165], v[216:219], v[4:7]
	s_setprio 0
	s_setprio 1
	v_mfma_f32_16x16x32_bf16 v[56:59], v[166:169], v[182:185], v[56:59]
	v_mfma_f32_16x16x32_bf16 v[48:51], v[174:177], v[182:185], v[48:51]
	v_mfma_f32_16x16x32_bf16 v[40:43], v[166:169], v[190:193], v[40:43]
	v_mfma_f32_16x16x32_bf16 v[32:35], v[174:177], v[190:193], v[32:35]
	v_mfma_f32_16x16x32_bf16 v[24:27], v[166:169], v[198:201], v[24:27]
	v_mfma_f32_16x16x32_bf16 v[16:19], v[174:177], v[198:201], v[16:19]
	v_mfma_f32_16x16x32_bf16 v[8:11], v[166:169], v[212:215], v[8:11]
	v_mfma_f32_16x16x32_bf16 v[0:3], v[174:177], v[212:215], v[0:3]
	v_mfma_f32_16x16x32_bf16 v[56:59], v[170:173], v[186:189], v[56:59]
	v_mfma_f32_16x16x32_bf16 v[48:51], v[178:181], v[186:189], v[48:51]
	v_mfma_f32_16x16x32_bf16 v[40:43], v[170:173], v[194:197], v[40:43]
	v_mfma_f32_16x16x32_bf16 v[32:35], v[178:181], v[194:197], v[32:35]
	v_mfma_f32_16x16x32_bf16 v[24:27], v[170:173], v[202:205], v[24:27]
	v_mfma_f32_16x16x32_bf16 v[16:19], v[178:181], v[202:205], v[16:19]
	v_mfma_f32_16x16x32_bf16 v[8:11], v[170:173], v[216:219], v[8:11]
	v_mfma_f32_16x16x32_bf16 v[0:3], v[178:181], v[216:219], v[0:3]
	s_setprio 0
	s_barrier
	s_add_i32 s58, 0, 0x18000
	s_add_i32 s59, 0, 0x1c000
	v_add_u32_e32 v162, s58, v149
	v_add_u32_e32 v178, s59, v149
	ds_read_b128 v[144:147], v162
	ds_read_b128 v[154:157], v162 offset:1024
	ds_read_b128 v[158:161], v162 offset:2048
	ds_read_b128 v[162:165], v162 offset:3072
	ds_read_b128 v[166:169], v178
	ds_read_b128 v[170:173], v178 offset:1024
	ds_read_b128 v[174:177], v178 offset:2048
	ds_read_b128 v[178:181], v178 offset:3072
	v_lshl_add_u64 v[222:223], s[42:43], 0, v[134:135]
	s_mov_b32 m0, s37
	s_nop 0
	global_load_lds_dwordx4 v[222:223], off
	s_mov_b32 m0, s47
	s_nop 0
	global_load_lds_dwordx4 v[224:225], off
	s_add_u32 s42, s42, 0x40000
	s_addc_u32 s43, s43, 0
	s_mov_b32 m0, s48
	v_lshl_add_u64 v[226:227], s[42:43], 0, v[134:135]
	ds_read_b128 v[182:185], v153 offset:32768
	ds_read_b128 v[186:189], v153 offset:33792
	ds_read_b128 v[190:193], v153 offset:34816
	ds_read_b128 v[194:197], v153 offset:35840
	ds_read_b128 v[198:201], v153 offset:36864
	ds_read_b128 v[202:205], v153 offset:37888
	ds_read_b128 v[212:215], v153 offset:38912
	ds_read_b128 v[216:219], v153 offset:39936
	global_load_lds_dwordx4 v[226:227], off
	v_lshl_add_u64 v[226:227], s[42:43], 0, v[130:131]
	s_mov_b32 m0, s49
	s_nop 0
	global_load_lds_dwordx4 v[226:227], off
	s_waitcnt vmcnt(8)
	s_waitcnt lgkmcnt(0)
	s_barrier
	s_setprio 1
	s_waitcnt lgkmcnt(0)
	v_mfma_f32_16x16x32_bf16 v[124:127], v[144:147], v[182:185], v[124:127]
	v_mfma_f32_16x16x32_bf16 v[116:119], v[158:161], v[182:185], v[116:119]
	v_mfma_f32_16x16x32_bf16 v[108:111], v[144:147], v[190:193], v[108:111]
	v_mfma_f32_16x16x32_bf16 v[100:103], v[158:161], v[190:193], v[100:103]
	v_mfma_f32_16x16x32_bf16 v[92:95], v[144:147], v[198:201], v[92:95]
	v_mfma_f32_16x16x32_bf16 v[84:87], v[158:161], v[198:201], v[84:87]
	v_mfma_f32_16x16x32_bf16 v[76:79], v[144:147], v[212:215], v[76:79]
	v_mfma_f32_16x16x32_bf16 v[68:71], v[158:161], v[212:215], v[68:71]
	v_mfma_f32_16x16x32_bf16 v[124:127], v[154:157], v[186:189], v[124:127]
	v_mfma_f32_16x16x32_bf16 v[116:119], v[162:165], v[186:189], v[116:119]
	v_mfma_f32_16x16x32_bf16 v[108:111], v[154:157], v[194:197], v[108:111]
	v_mfma_f32_16x16x32_bf16 v[100:103], v[162:165], v[194:197], v[100:103]
	v_mfma_f32_16x16x32_bf16 v[92:95], v[154:157], v[202:205], v[92:95]
	v_mfma_f32_16x16x32_bf16 v[84:87], v[162:165], v[202:205], v[84:87]
	v_mfma_f32_16x16x32_bf16 v[76:79], v[154:157], v[216:219], v[76:79]
	v_mfma_f32_16x16x32_bf16 v[68:71], v[162:165], v[216:219], v[68:71]
	s_setprio 0
	s_setprio 1
	v_mfma_f32_16x16x32_bf16 v[120:123], v[166:169], v[182:185], v[120:123]
	v_mfma_f32_16x16x32_bf16 v[112:115], v[174:177], v[182:185], v[112:115]
	v_mfma_f32_16x16x32_bf16 v[104:107], v[166:169], v[190:193], v[104:107]
	v_mfma_f32_16x16x32_bf16 v[96:99], v[174:177], v[190:193], v[96:99]
	v_mfma_f32_16x16x32_bf16 v[88:91], v[166:169], v[198:201], v[88:91]
	v_mfma_f32_16x16x32_bf16 v[80:83], v[174:177], v[198:201], v[80:83]
	v_mfma_f32_16x16x32_bf16 v[72:75], v[166:169], v[212:215], v[72:75]
	v_mfma_f32_16x16x32_bf16 v[64:67], v[174:177], v[212:215], v[64:67]
	v_mfma_f32_16x16x32_bf16 v[120:123], v[170:173], v[186:189], v[120:123]
	v_mfma_f32_16x16x32_bf16 v[112:115], v[178:181], v[186:189], v[112:115]
	v_mfma_f32_16x16x32_bf16 v[104:107], v[170:173], v[194:197], v[104:107]
	v_mfma_f32_16x16x32_bf16 v[96:99], v[178:181], v[194:197], v[96:99]
	v_mfma_f32_16x16x32_bf16 v[88:91], v[170:173], v[202:205], v[88:91]
	v_mfma_f32_16x16x32_bf16 v[80:83], v[178:181], v[202:205], v[80:83]
	v_mfma_f32_16x16x32_bf16 v[72:75], v[170:173], v[216:219], v[72:75]
	v_mfma_f32_16x16x32_bf16 v[64:67], v[178:181], v[216:219], v[64:67]
	s_setprio 0
	s_barrier
	s_add_i32 s42, s58, s44
	v_lshl_add_u64 v[206:207], v[206:207], 0, s[6:7]
	s_mov_b32 m0, s42
	ds_read_b128 v[182:185], v153 offset:49152
	ds_read_b128 v[186:189], v153 offset:50176
	ds_read_b128 v[190:193], v153 offset:51200
	ds_read_b128 v[194:197], v153 offset:52224
	ds_read_b128 v[198:201], v153 offset:53248
	ds_read_b128 v[202:205], v153 offset:54272
	ds_read_b128 v[212:215], v153 offset:55296
	ds_read_b128 v[216:219], v153 offset:56320
	global_load_lds_dwordx4 v[206:207], off
	s_add_i32 m0, s42, 0x2000
	s_add_u32 s40, s40, 0x40080
	v_lshl_add_u64 v[206:207], v[220:221], 0, s[6:7]
	s_addc_u32 s41, s41, 0
	s_add_i32 s42, s59, s44
	global_load_lds_dwordx4 v[206:207], off
	v_lshl_add_u64 v[206:207], s[40:41], 0, v[132:133]
	s_mov_b32 m0, s42
	s_nop 0
	global_load_lds_dwordx4 v[206:207], off
	v_lshl_add_u64 v[206:207], s[40:41], 0, v[128:129]
	s_add_i32 m0, s42, 0x2000
	s_nop 0
	global_load_lds_dwordx4 v[206:207], off
	v_lshl_add_u64 v[206:207], v[222:223], 0, s[6:7]
	s_mov_b32 m0, s51
	s_nop 0
	global_load_lds_dwordx4 v[206:207], off
	v_lshl_add_u64 v[206:207], v[224:225], 0, s[6:7]
	s_mov_b32 m0, s52
	s_nop 0
	global_load_lds_dwordx4 v[206:207], off
	s_waitcnt vmcnt(6)
	s_waitcnt lgkmcnt(0)
	s_barrier
	s_setprio 1
	s_waitcnt lgkmcnt(0)
	v_mfma_f32_16x16x32_bf16 v[60:63], v[144:147], v[182:185], v[60:63]
	v_mfma_f32_16x16x32_bf16 v[52:55], v[158:161], v[182:185], v[52:55]
	v_mfma_f32_16x16x32_bf16 v[44:47], v[144:147], v[190:193], v[44:47]
	v_mfma_f32_16x16x32_bf16 v[36:39], v[158:161], v[190:193], v[36:39]
	v_mfma_f32_16x16x32_bf16 v[28:31], v[144:147], v[198:201], v[28:31]
	v_mfma_f32_16x16x32_bf16 v[20:23], v[158:161], v[198:201], v[20:23]
	v_mfma_f32_16x16x32_bf16 v[12:15], v[144:147], v[212:215], v[12:15]
	v_mfma_f32_16x16x32_bf16 v[4:7], v[158:161], v[212:215], v[4:7]
	v_mfma_f32_16x16x32_bf16 v[60:63], v[154:157], v[186:189], v[60:63]
	v_mfma_f32_16x16x32_bf16 v[52:55], v[162:165], v[186:189], v[52:55]
	v_mfma_f32_16x16x32_bf16 v[44:47], v[154:157], v[194:197], v[44:47]
	v_mfma_f32_16x16x32_bf16 v[36:39], v[162:165], v[194:197], v[36:39]
	v_mfma_f32_16x16x32_bf16 v[28:31], v[154:157], v[202:205], v[28:31]
	v_mfma_f32_16x16x32_bf16 v[20:23], v[162:165], v[202:205], v[20:23]
	v_mfma_f32_16x16x32_bf16 v[12:15], v[154:157], v[216:219], v[12:15]
	v_mfma_f32_16x16x32_bf16 v[4:7], v[162:165], v[216:219], v[4:7]
	s_setprio 0
	s_setprio 1
	v_mfma_f32_16x16x32_bf16 v[56:59], v[166:169], v[182:185], v[56:59]
	v_mfma_f32_16x16x32_bf16 v[48:51], v[174:177], v[182:185], v[48:51]
	v_mfma_f32_16x16x32_bf16 v[40:43], v[166:169], v[190:193], v[40:43]
	v_mfma_f32_16x16x32_bf16 v[32:35], v[174:177], v[190:193], v[32:35]
	v_mfma_f32_16x16x32_bf16 v[24:27], v[166:169], v[198:201], v[24:27]
	v_mfma_f32_16x16x32_bf16 v[16:19], v[174:177], v[198:201], v[16:19]
	v_mfma_f32_16x16x32_bf16 v[8:11], v[166:169], v[212:215], v[8:11]
	v_mfma_f32_16x16x32_bf16 v[0:3], v[174:177], v[212:215], v[0:3]
	v_mfma_f32_16x16x32_bf16 v[56:59], v[170:173], v[186:189], v[56:59]
	v_mfma_f32_16x16x32_bf16 v[48:51], v[178:181], v[186:189], v[48:51]
	v_mfma_f32_16x16x32_bf16 v[40:43], v[170:173], v[194:197], v[40:43]
	v_mfma_f32_16x16x32_bf16 v[32:35], v[178:181], v[194:197], v[32:35]
	v_mfma_f32_16x16x32_bf16 v[24:27], v[170:173], v[202:205], v[24:27]
	v_mfma_f32_16x16x32_bf16 v[16:19], v[178:181], v[202:205], v[16:19]
	v_mfma_f32_16x16x32_bf16 v[8:11], v[170:173], v[216:219], v[8:11]
	v_mfma_f32_16x16x32_bf16 v[0:3], v[178:181], v[216:219], v[0:3]
	s_setprio 0
	s_barrier
	s_add_i32 s68, s68, 2
	s_add_u32 s38, s38, 0x100
	s_addc_u32 s39, s39, 0
	s_add_u32 s67, s67, 0x100
	s_addc_u32 s33, s33, 0
	s_cmp_gt_u32 s68, 13
	s_cbranch_scc0 .LBB0_639
	s_and_b64 vcc, exec, s[8:9]
	s_cbranch_vccz .LBB0_642
	s_barrier

.LBB0_722:
	ds_read_b128 v[96:99], v185
	ds_read_b128 v[100:103], v185 offset:1024
	ds_read_b128 v[104:107], v185 offset:2048
	ds_read_b128 v[108:111], v185 offset:3072
	ds_read_b128 v[156:159], v186
	ds_read_b128 v[160:163], v186 offset:1024
	ds_read_b128 v[164:167], v186 offset:2048
	ds_read_b128 v[168:171], v186 offset:3072
	s_add_u32 s28, s26, 0x100
	s_addc_u32 s29, s27, 0
	s_cmp_eq_u32 s57, 40
	s_cselect_b32 s37, s7, s29
	s_cselect_b32 s36, s6, s28
	s_cselect_b32 s35, s23, s56
	s_cselect_b32 s34, s22, s55
	v_lshl_add_u64 v[180:181], s[26:27], 0, v[148:149]
	s_add_i32 m0, s15, 0xc000
	ds_read_b128 v[172:175], v187
	ds_read_b128 v[176:179], v187 offset:1024
	ds_read_b128 v[190:193], v187 offset:2048
	ds_read_b128 v[194:197], v187 offset:3072
	ds_read_b128 v[198:201], v187 offset:4096
	ds_read_b128 v[202:205], v187 offset:5120
	ds_read_b128 v[206:209], v187 offset:6144
	ds_read_b128 v[212:215], v187 offset:7168
	global_load_lds_dwordx4 v[180:181], off
	v_lshl_add_u64 v[180:181], s[26:27], 0, v[150:151]
	s_add_i32 m0, s15, 0xe000
	s_nop 0
	global_load_lds_dwordx4 v[180:181], off
	s_waitcnt vmcnt(8)
	s_waitcnt lgkmcnt(0)
	s_barrier
	s_setprio 1
	s_waitcnt lgkmcnt(0)
	v_mfma_f32_16x16x32_bf16 v[140:143], v[96:99], v[172:175], v[140:143]
	v_mfma_f32_16x16x32_bf16 v[136:139], v[104:107], v[172:175], v[136:139]
	v_mfma_f32_16x16x32_bf16 v[124:127], v[96:99], v[190:193], v[124:127]
	v_mfma_f32_16x16x32_bf16 v[120:123], v[104:107], v[190:193], v[120:123]
	v_mfma_f32_16x16x32_bf16 v[92:95], v[96:99], v[198:201], v[92:95]
	v_mfma_f32_16x16x32_bf16 v[88:91], v[104:107], v[198:201], v[88:91]
	v_mfma_f32_16x16x32_bf16 v[76:79], v[96:99], v[206:209], v[76:79]
	v_mfma_f32_16x16x32_bf16 v[72:75], v[104:107], v[206:209], v[72:75]
	v_mfma_f32_16x16x32_bf16 v[140:143], v[100:103], v[176:179], v[140:143]
	v_mfma_f32_16x16x32_bf16 v[136:139], v[108:111], v[176:179], v[136:139]
	v_mfma_f32_16x16x32_bf16 v[124:127], v[100:103], v[194:197], v[124:127]
	v_mfma_f32_16x16x32_bf16 v[120:123], v[108:111], v[194:197], v[120:123]
	v_mfma_f32_16x16x32_bf16 v[92:95], v[100:103], v[202:205], v[92:95]
	v_mfma_f32_16x16x32_bf16 v[88:91], v[108:111], v[202:205], v[88:91]
	v_mfma_f32_16x16x32_bf16 v[76:79], v[100:103], v[212:215], v[76:79]
	v_mfma_f32_16x16x32_bf16 v[72:75], v[108:111], v[212:215], v[72:75]
	s_setprio 0
	s_setprio 1
	v_mfma_f32_16x16x32_bf16 v[132:135], v[156:159], v[172:175], v[132:135]
	v_mfma_f32_16x16x32_bf16 v[128:131], v[164:167], v[172:175], v[128:131]
	v_mfma_f32_16x16x32_bf16 v[116:119], v[156:159], v[190:193], v[116:119]
	v_mfma_f32_16x16x32_bf16 v[112:115], v[164:167], v[190:193], v[112:115]
	v_mfma_f32_16x16x32_bf16 v[84:87], v[156:159], v[198:201], v[84:87]
	v_mfma_f32_16x16x32_bf16 v[80:83], v[164:167], v[198:201], v[80:83]
	v_mfma_f32_16x16x32_bf16 v[68:71], v[156:159], v[206:209], v[68:71]
	v_mfma_f32_16x16x32_bf16 v[64:67], v[164:167], v[206:209], v[64:67]
	v_mfma_f32_16x16x32_bf16 v[132:135], v[160:163], v[176:179], v[132:135]
	v_mfma_f32_16x16x32_bf16 v[128:131], v[168:171], v[176:179], v[128:131]
	v_mfma_f32_16x16x32_bf16 v[116:119], v[160:163], v[194:197], v[116:119]
	v_mfma_f32_16x16x32_bf16 v[112:115], v[168:171], v[194:197], v[112:115]
	v_mfma_f32_16x16x32_bf16 v[84:87], v[160:163], v[202:205], v[84:87]
	v_mfma_f32_16x16x32_bf16 v[80:83], v[168:171], v[202:205], v[80:83]
	v_mfma_f32_16x16x32_bf16 v[68:71], v[160:163], v[212:215], v[68:71]
	v_mfma_f32_16x16x32_bf16 v[64:67], v[168:171], v[212:215], v[64:67]
	s_setprio 0
	s_barrier
	s_add_i32 s26, s49, s3
	v_lshl_add_u64 v[180:181], s[34:35], 0, v[144:145]
	s_mov_b32 m0, s26
	ds_read_b128 v[172:175], v187 offset:16384
	ds_read_b128 v[176:179], v187 offset:17408
	ds_read_b128 v[190:193], v187 offset:18432
	ds_read_b128 v[194:197], v187 offset:19456
	ds_read_b128 v[198:201], v187 offset:20480
	ds_read_b128 v[202:205], v187 offset:21504
	ds_read_b128 v[206:209], v187 offset:22528
	ds_read_b128 v[212:215], v187 offset:23552
	global_load_lds_dwordx4 v[180:181], off
	s_add_i32 m0, s26, 0x2000
	s_add_u32 s26, s34, 0xb0000
	v_lshl_add_u64 v[216:217], s[34:35], 0, v[146:147]
	s_addc_u32 s27, s35, 0
	s_add_i32 s58, s50, s3
	global_load_lds_dwordx4 v[216:217], off
	v_lshl_add_u64 v[218:219], s[26:27], 0, v[144:145]
	s_mov_b32 m0, s58
	v_lshl_add_u64 v[220:221], s[36:37], 0, v[146:147]
	global_load_lds_dwordx4 v[218:219], off
	v_lshl_add_u64 v[218:219], s[26:27], 0, v[146:147]
	s_add_i32 m0, s58, 0x2000
	s_nop 0
	global_load_lds_dwordx4 v[218:219], off
	s_waitcnt vmcnt(6)
	s_waitcnt lgkmcnt(0)
	s_barrier
	s_setprio 1
	s_waitcnt lgkmcnt(0)
	v_mfma_f32_16x16x32_bf16 v[60:63], v[96:99], v[172:175], v[60:63]
	v_mfma_f32_16x16x32_bf16 v[56:59], v[104:107], v[172:175], v[56:59]
	v_mfma_f32_16x16x32_bf16 v[44:47], v[96:99], v[190:193], v[44:47]
	v_mfma_f32_16x16x32_bf16 v[40:43], v[104:107], v[190:193], v[40:43]
	v_mfma_f32_16x16x32_bf16 v[28:31], v[96:99], v[198:201], v[28:31]
	v_mfma_f32_16x16x32_bf16 v[24:27], v[104:107], v[198:201], v[24:27]
	v_mfma_f32_16x16x32_bf16 v[12:15], v[96:99], v[206:209], v[12:15]
	v_mfma_f32_16x16x32_bf16 v[8:11], v[104:107], v[206:209], v[8:11]
	v_mfma_f32_16x16x32_bf16 v[60:63], v[100:103], v[176:179], v[60:63]
	v_mfma_f32_16x16x32_bf16 v[56:59], v[108:111], v[176:179], v[56:59]
	v_mfma_f32_16x16x32_bf16 v[44:47], v[100:103], v[194:197], v[44:47]
	v_mfma_f32_16x16x32_bf16 v[40:43], v[108:111], v[194:197], v[40:43]
	v_mfma_f32_16x16x32_bf16 v[28:31], v[100:103], v[202:205], v[28:31]
	v_mfma_f32_16x16x32_bf16 v[24:27], v[108:111], v[202:205], v[24:27]
	v_mfma_f32_16x16x32_bf16 v[12:15], v[100:103], v[212:215], v[12:15]
	v_mfma_f32_16x16x32_bf16 v[8:11], v[108:111], v[212:215], v[8:11]
	s_setprio 0
	s_setprio 1
	v_mfma_f32_16x16x32_bf16 v[52:55], v[156:159], v[172:175], v[52:55]
	v_mfma_f32_16x16x32_bf16 v[48:51], v[164:167], v[172:175], v[48:51]
	v_mfma_f32_16x16x32_bf16 v[36:39], v[156:159], v[190:193], v[36:39]
	v_mfma_f32_16x16x32_bf16 v[32:35], v[164:167], v[190:193], v[32:35]
	v_mfma_f32_16x16x32_bf16 v[20:23], v[156:159], v[198:201], v[20:23]
	v_mfma_f32_16x16x32_bf16 v[16:19], v[164:167], v[198:201], v[16:19]
	v_mfma_f32_16x16x32_bf16 v[4:7], v[156:159], v[206:209], v[4:7]
	v_mfma_f32_16x16x32_bf16 v[0:3], v[164:167], v[206:209], v[0:3]
	v_mfma_f32_16x16x32_bf16 v[52:55], v[160:163], v[176:179], v[52:55]
	v_mfma_f32_16x16x32_bf16 v[48:51], v[168:171], v[176:179], v[48:51]
	v_mfma_f32_16x16x32_bf16 v[36:39], v[160:163], v[194:197], v[36:39]
	v_mfma_f32_16x16x32_bf16 v[32:35], v[168:171], v[194:197], v[32:35]
	v_mfma_f32_16x16x32_bf16 v[20:23], v[160:163], v[202:205], v[20:23]
	v_mfma_f32_16x16x32_bf16 v[16:19], v[168:171], v[202:205], v[16:19]
	v_mfma_f32_16x16x32_bf16 v[4:7], v[160:163], v[212:215], v[4:7]
	v_mfma_f32_16x16x32_bf16 v[0:3], v[168:171], v[212:215], v[0:3]
	s_setprio 0
	s_barrier
	s_add_i32 s58, 0, 0x18000
	s_add_i32 s59, 0, 0x1c000
	v_add_u32_e32 v108, s58, v183
	v_add_u32_e32 v168, s59, v183
	ds_read_b128 v[96:99], v108
	ds_read_b128 v[100:103], v108 offset:1024
	ds_read_b128 v[104:107], v108 offset:2048
	ds_read_b128 v[108:111], v108 offset:3072
	ds_read_b128 v[156:159], v168
	ds_read_b128 v[160:163], v168 offset:1024
	ds_read_b128 v[164:167], v168 offset:2048
	ds_read_b128 v[168:171], v168 offset:3072
	v_lshl_add_u64 v[218:219], s[36:37], 0, v[144:145]
	s_mov_b32 m0, s15
	s_nop 0
	global_load_lds_dwordx4 v[218:219], off
	s_mov_b32 m0, s33
	s_nop 0
	global_load_lds_dwordx4 v[220:221], off
	s_add_u32 s26, s36, 0xb0000
	s_addc_u32 s27, s37, 0
	s_mov_b32 m0, s38
	v_lshl_add_u64 v[222:223], s[26:27], 0, v[144:145]
	ds_read_b128 v[172:175], v187 offset:32768
	ds_read_b128 v[176:179], v187 offset:33792
	ds_read_b128 v[190:193], v187 offset:34816
	ds_read_b128 v[194:197], v187 offset:35840
	ds_read_b128 v[198:201], v187 offset:36864
	ds_read_b128 v[202:205], v187 offset:37888
	ds_read_b128 v[206:209], v187 offset:38912
	ds_read_b128 v[212:215], v187 offset:39936
	global_load_lds_dwordx4 v[222:223], off
	v_lshl_add_u64 v[222:223], s[26:27], 0, v[146:147]
	s_mov_b32 m0, s39
	s_nop 0
	global_load_lds_dwordx4 v[222:223], off
	s_waitcnt vmcnt(8)
	s_waitcnt lgkmcnt(0)
	s_barrier
	s_setprio 1
	s_waitcnt lgkmcnt(0)
	v_mfma_f32_16x16x32_bf16 v[140:143], v[96:99], v[172:175], v[140:143]
	v_mfma_f32_16x16x32_bf16 v[136:139], v[104:107], v[172:175], v[136:139]
	v_mfma_f32_16x16x32_bf16 v[124:127], v[96:99], v[190:193], v[124:127]
	v_mfma_f32_16x16x32_bf16 v[120:123], v[104:107], v[190:193], v[120:123]
	v_mfma_f32_16x16x32_bf16 v[92:95], v[96:99], v[198:201], v[92:95]
	v_mfma_f32_16x16x32_bf16 v[88:91], v[104:107], v[198:201], v[88:91]
	v_mfma_f32_16x16x32_bf16 v[76:79], v[96:99], v[206:209], v[76:79]
	v_mfma_f32_16x16x32_bf16 v[72:75], v[104:107], v[206:209], v[72:75]
	v_mfma_f32_16x16x32_bf16 v[140:143], v[100:103], v[176:179], v[140:143]
	v_mfma_f32_16x16x32_bf16 v[136:139], v[108:111], v[176:179], v[136:139]
	v_mfma_f32_16x16x32_bf16 v[124:127], v[100:103], v[194:197], v[124:127]
	v_mfma_f32_16x16x32_bf16 v[120:123], v[108:111], v[194:197], v[120:123]
	v_mfma_f32_16x16x32_bf16 v[92:95], v[100:103], v[202:205], v[92:95]
	v_mfma_f32_16x16x32_bf16 v[88:91], v[108:111], v[202:205], v[88:91]
	v_mfma_f32_16x16x32_bf16 v[76:79], v[100:103], v[212:215], v[76:79]
	v_mfma_f32_16x16x32_bf16 v[72:75], v[108:111], v[212:215], v[72:75]
	s_setprio 0
	s_setprio 1
	v_mfma_f32_16x16x32_bf16 v[132:135], v[156:159], v[172:175], v[132:135]
	v_mfma_f32_16x16x32_bf16 v[128:131], v[164:167], v[172:175], v[128:131]
	v_mfma_f32_16x16x32_bf16 v[116:119], v[156:159], v[190:193], v[116:119]
	v_mfma_f32_16x16x32_bf16 v[112:115], v[164:167], v[190:193], v[112:115]
	v_mfma_f32_16x16x32_bf16 v[84:87], v[156:159], v[198:201], v[84:87]
	v_mfma_f32_16x16x32_bf16 v[80:83], v[164:167], v[198:201], v[80:83]
	v_mfma_f32_16x16x32_bf16 v[68:71], v[156:159], v[206:209], v[68:71]
	v_mfma_f32_16x16x32_bf16 v[64:67], v[164:167], v[206:209], v[64:67]
	v_mfma_f32_16x16x32_bf16 v[132:135], v[160:163], v[176:179], v[132:135]
	v_mfma_f32_16x16x32_bf16 v[128:131], v[168:171], v[176:179], v[128:131]
	v_mfma_f32_16x16x32_bf16 v[116:119], v[160:163], v[194:197], v[116:119]
	v_mfma_f32_16x16x32_bf16 v[112:115], v[168:171], v[194:197], v[112:115]
	v_mfma_f32_16x16x32_bf16 v[84:87], v[160:163], v[202:205], v[84:87]
	v_mfma_f32_16x16x32_bf16 v[80:83], v[168:171], v[202:205], v[80:83]
	v_mfma_f32_16x16x32_bf16 v[68:71], v[160:163], v[212:215], v[68:71]
	v_mfma_f32_16x16x32_bf16 v[64:67], v[168:171], v[212:215], v[64:67]
	s_setprio 0
	s_barrier
	s_add_i32 s26, s58, s3
	v_lshl_add_u64 v[180:181], v[180:181], 0, s[16:17]
	s_mov_b32 m0, s26
	ds_read_b128 v[172:175], v187 offset:49152
	ds_read_b128 v[176:179], v187 offset:50176
	ds_read_b128 v[190:193], v187 offset:51200
	ds_read_b128 v[194:197], v187 offset:52224
	ds_read_b128 v[198:201], v187 offset:53248
	ds_read_b128 v[202:205], v187 offset:54272
	ds_read_b128 v[206:209], v187 offset:55296
	ds_read_b128 v[212:215], v187 offset:56320
	global_load_lds_dwordx4 v[180:181], off
	s_add_i32 m0, s26, 0x2000
	s_add_u32 s26, s34, 0xb0080
	v_lshl_add_u64 v[180:181], v[216:217], 0, s[16:17]
	s_addc_u32 s27, s35, 0
	s_add_i32 s34, s59, s3
	global_load_lds_dwordx4 v[180:181], off
	v_lshl_add_u64 v[180:181], s[26:27], 0, v[144:145]
	s_mov_b32 m0, s34
	s_nop 0
	global_load_lds_dwordx4 v[180:181], off
	v_lshl_add_u64 v[180:181], s[26:27], 0, v[146:147]
	s_add_i32 m0, s34, 0x2000
	s_nop 0
	global_load_lds_dwordx4 v[180:181], off
	v_lshl_add_u64 v[180:181], v[218:219], 0, s[16:17]
	s_mov_b32 m0, s45
	s_nop 0
	global_load_lds_dwordx4 v[180:181], off
	v_lshl_add_u64 v[180:181], v[220:221], 0, s[16:17]
	s_mov_b32 m0, s46
	s_nop 0
	global_load_lds_dwordx4 v[180:181], off
	s_waitcnt vmcnt(6)
	s_waitcnt lgkmcnt(0)
	s_barrier
	s_setprio 1
	s_waitcnt lgkmcnt(0)
	v_mfma_f32_16x16x32_bf16 v[60:63], v[96:99], v[172:175], v[60:63]
	v_mfma_f32_16x16x32_bf16 v[56:59], v[104:107], v[172:175], v[56:59]
	v_mfma_f32_16x16x32_bf16 v[44:47], v[96:99], v[190:193], v[44:47]
	v_mfma_f32_16x16x32_bf16 v[40:43], v[104:107], v[190:193], v[40:43]
	v_mfma_f32_16x16x32_bf16 v[28:31], v[96:99], v[198:201], v[28:31]
	v_mfma_f32_16x16x32_bf16 v[24:27], v[104:107], v[198:201], v[24:27]
	v_mfma_f32_16x16x32_bf16 v[12:15], v[96:99], v[206:209], v[12:15]
	v_mfma_f32_16x16x32_bf16 v[8:11], v[104:107], v[206:209], v[8:11]
	v_mfma_f32_16x16x32_bf16 v[60:63], v[100:103], v[176:179], v[60:63]
	v_mfma_f32_16x16x32_bf16 v[56:59], v[108:111], v[176:179], v[56:59]
	v_mfma_f32_16x16x32_bf16 v[44:47], v[100:103], v[194:197], v[44:47]
	v_mfma_f32_16x16x32_bf16 v[40:43], v[108:111], v[194:197], v[40:43]
	v_mfma_f32_16x16x32_bf16 v[28:31], v[100:103], v[202:205], v[28:31]
	v_mfma_f32_16x16x32_bf16 v[24:27], v[108:111], v[202:205], v[24:27]
	v_mfma_f32_16x16x32_bf16 v[12:15], v[100:103], v[212:215], v[12:15]
	v_mfma_f32_16x16x32_bf16 v[8:11], v[108:111], v[212:215], v[8:11]
	s_setprio 0
	s_setprio 1
	v_mfma_f32_16x16x32_bf16 v[52:55], v[156:159], v[172:175], v[52:55]
	v_mfma_f32_16x16x32_bf16 v[48:51], v[164:167], v[172:175], v[48:51]
	v_mfma_f32_16x16x32_bf16 v[36:39], v[156:159], v[190:193], v[36:39]
	v_mfma_f32_16x16x32_bf16 v[32:35], v[164:167], v[190:193], v[32:35]
	v_mfma_f32_16x16x32_bf16 v[20:23], v[156:159], v[198:201], v[20:23]
	v_mfma_f32_16x16x32_bf16 v[16:19], v[164:167], v[198:201], v[16:19]
	v_mfma_f32_16x16x32_bf16 v[4:7], v[156:159], v[206:209], v[4:7]
	v_mfma_f32_16x16x32_bf16 v[0:3], v[164:167], v[206:209], v[0:3]
	v_mfma_f32_16x16x32_bf16 v[52:55], v[160:163], v[176:179], v[52:55]
	v_mfma_f32_16x16x32_bf16 v[48:51], v[168:171], v[176:179], v[48:51]
	v_mfma_f32_16x16x32_bf16 v[36:39], v[160:163], v[194:197], v[36:39]
	v_mfma_f32_16x16x32_bf16 v[32:35], v[168:171], v[194:197], v[32:35]
	v_mfma_f32_16x16x32_bf16 v[20:23], v[160:163], v[202:205], v[20:23]
	v_mfma_f32_16x16x32_bf16 v[16:19], v[168:171], v[202:205], v[16:19]
	v_mfma_f32_16x16x32_bf16 v[4:7], v[160:163], v[212:215], v[4:7]
	v_mfma_f32_16x16x32_bf16 v[0:3], v[168:171], v[212:215], v[0:3]
	s_setprio 0
	s_barrier
	s_add_i32 s57, s57, 2
	s_add_u32 s55, s55, 0x100
	s_addc_u32 s56, s56, 0
	s_cmp_gt_u32 s57, 41
	s_mov_b64 s[26:27], s[28:29]
	s_cbranch_scc0 .LBB0_722
	s_and_b64 vcc, exec, s[20:21]
	s_cbranch_vccz .LBB0_725
	s_barrier
